# strategy 4: one static s_setprio 1 for the younger wave half (waves 4-7) at kernel entry, per-MMA-block priority toggles removed from the six GEMM main loops
# baseline (speedup 1.0000x reference)
_Z8mega_fwd6Params:
	s_load_dwordx2 s[14:15], s[0:1], 0x140
	s_add_u32 s12, s0, 0x140
	v_and_b32_e32 v179, 0x3ff, v0
	s_mov_b32 s10, s2
	s_addc_u32 s13, s1, 0
	v_readfirstlane_b32 s4, v179
	s_cmpk_lt_u32 s4, 0x100
	s_cbranch_scc1 .Lprio_older_half
	s_setprio 1
.Lprio_older_half:
	v_cmp_gt_u32_e32 vcc, 2, v179
	s_and_saveexec_b64 s[4:5], vcc
	v_lshl_add_u32 v1, v179, 2, 0
	v_add_u32_e32 v1, 0x23ff0, v1
	v_mov_b32_e32 v2, 0
	ds_write_b32 v1, v2
	s_or_b64 exec, exec, s[4:5]
	s_load_dwordx2 s[26:27], s[0:1], 0x138
	s_waitcnt lgkmcnt(0)
	s_barrier
	s_getreg_b32 s2, hwreg(HW_REG_XCC_ID, 0, 4)
	v_cmp_eq_u32_e64 s[6:7], 0, v179
	s_mov_b64 s[4:5], exec
	s_nop 0
	v_writelane_b32 v254, s6, 0
	s_nop 1
	v_writelane_b32 v254, s7, 1
	s_and_b64 s[6:7], s[4:5], s[6:7]
	s_mov_b64 exec, s[6:7]
	s_cbranch_execz .LBB0_5
	s_mov_b64 s[6:7], exec
	v_mbcnt_lo_u32_b32 v1, s6, 0
	v_mbcnt_hi_u32_b32 v1, s7, v1
	v_cmp_eq_u32_e32 vcc, 0, v1
	s_and_b64 s[8:9], exec, vcc
	s_mov_b64 exec, s[8:9]
	s_cbranch_execz .LBB0_5
	s_lshl_b32 s2, s2, 8
	s_and_b32 s2, s2, 0xf00
	s_add_u32 s2, s26, s2
	s_addc_u32 s3, s27, 0
	s_bcnt1_i32_b64 s6, s[6:7]
	v_mov_b32_e32 v1, 0x10000
	v_mov_b32_e32 v2, s6
	global_atomic_add v1, v2, s[2:3] offset:1024

.LBB0_183:
	s_add_u32 s34, s6, 0xfffc0080
	s_addc_u32 s35, s7, -1
	s_add_i32 s67, 0, 0x10000
	s_cmp_eq_u32 s66, 12
	s_cselect_b32 s39, s21, s35
	s_cselect_b32 s38, s61, s34
	s_cselect_b32 s35, s17, s65
	s_cselect_b32 s34, s62, s64
	s_add_i32 s70, 0, 0x14000
	v_add_u32_e32 v142, s67, v171
	v_add_u32_e32 v166, s70, v171
	ds_read_b128 v[130:133], v142
	ds_read_b128 v[134:137], v142 offset:1024
	ds_read_b128 v[138:141], v142 offset:2048
	ds_read_b128 v[142:145], v142 offset:3072
	ds_read_b128 v[146:149], v166
	ds_read_b128 v[162:165], v166 offset:1024
	ds_read_b128 v[172:175], v166 offset:2048
	ds_read_b128 v[184:187], v166 offset:3072
	v_lshl_add_u64 v[166:167], s[6:7], 0, v[158:159]
	s_add_i32 m0, s49, 0xc000
	ds_read_b128 v[190:193], v189
	ds_read_b128 v[194:197], v189 offset:1024
	ds_read_b128 v[198:201], v189 offset:2048
	ds_read_b128 v[202:205], v189 offset:3072
	ds_read_b128 v[206:209], v189 offset:4096
	ds_read_b128 v[210:213], v189 offset:5120
	ds_read_b128 v[214:217], v189 offset:6144
	ds_read_b128 v[218:221], v189 offset:7168
	global_load_lds_dwordx4 v[166:167], off
	v_lshl_add_u64 v[166:167], s[6:7], 0, v[160:161]
	s_add_i32 m0, s49, 0xe000
	s_nop 0
	global_load_lds_dwordx4 v[166:167], off
	s_waitcnt vmcnt(8)
	s_waitcnt lgkmcnt(0)
	s_barrier
	s_waitcnt lgkmcnt(0)
	v_mfma_f32_16x16x32_bf16 v[126:129], v[130:133], v[190:193], v[126:129]
	v_mfma_f32_16x16x32_bf16 v[122:125], v[138:141], v[190:193], v[122:125]
	v_mfma_f32_16x16x32_bf16 v[118:121], v[130:133], v[198:201], v[118:121]
	v_mfma_f32_16x16x32_bf16 v[110:113], v[138:141], v[198:201], v[110:113]
	v_mfma_f32_16x16x32_bf16 v[102:105], v[130:133], v[206:209], v[102:105]
	v_mfma_f32_16x16x32_bf16 v[94:97], v[138:141], v[206:209], v[94:97]
	v_mfma_f32_16x16x32_bf16 v[86:89], v[130:133], v[214:217], v[86:89]
	v_mfma_f32_16x16x32_bf16 v[78:81], v[138:141], v[214:217], v[78:81]
	v_mfma_f32_16x16x32_bf16 v[126:129], v[134:137], v[194:197], v[126:129]
	v_mfma_f32_16x16x32_bf16 v[122:125], v[142:145], v[194:197], v[122:125]
	v_mfma_f32_16x16x32_bf16 v[118:121], v[134:137], v[202:205], v[118:121]
	v_mfma_f32_16x16x32_bf16 v[110:113], v[142:145], v[202:205], v[110:113]
	v_mfma_f32_16x16x32_bf16 v[102:105], v[134:137], v[210:213], v[102:105]
	v_mfma_f32_16x16x32_bf16 v[94:97], v[142:145], v[210:213], v[94:97]
	v_mfma_f32_16x16x32_bf16 v[86:89], v[134:137], v[218:221], v[86:89]
	v_mfma_f32_16x16x32_bf16 v[78:81], v[142:145], v[218:221], v[78:81]
	v_mfma_f32_16x16x32_bf16 v[114:117], v[146:149], v[190:193], v[114:117]
	v_mfma_f32_16x16x32_bf16 v[106:109], v[172:175], v[190:193], v[106:109]
	v_mfma_f32_16x16x32_bf16 v[98:101], v[146:149], v[198:201], v[98:101]
	v_mfma_f32_16x16x32_bf16 v[90:93], v[172:175], v[198:201], v[90:93]
	v_mfma_f32_16x16x32_bf16 v[82:85], v[146:149], v[206:209], v[82:85]
	v_mfma_f32_16x16x32_bf16 v[74:77], v[172:175], v[206:209], v[74:77]
	v_mfma_f32_16x16x32_bf16 v[70:73], v[146:149], v[214:217], v[70:73]
	v_mfma_f32_16x16x32_bf16 v[66:69], v[172:175], v[214:217], v[66:69]
	v_mfma_f32_16x16x32_bf16 v[114:117], v[162:165], v[194:197], v[114:117]
	v_mfma_f32_16x16x32_bf16 v[106:109], v[184:187], v[194:197], v[106:109]
	v_mfma_f32_16x16x32_bf16 v[98:101], v[162:165], v[202:205], v[98:101]
	v_mfma_f32_16x16x32_bf16 v[90:93], v[184:187], v[202:205], v[90:93]
	v_mfma_f32_16x16x32_bf16 v[82:85], v[162:165], v[210:213], v[82:85]
	v_mfma_f32_16x16x32_bf16 v[74:77], v[184:187], v[210:213], v[74:77]
	v_mfma_f32_16x16x32_bf16 v[70:73], v[162:165], v[218:221], v[70:73]
	v_mfma_f32_16x16x32_bf16 v[66:69], v[184:187], v[218:221], v[66:69]
	s_barrier
	s_add_i32 s67, s67, s48
	v_lshl_add_u64 v[166:167], s[34:35], 0, v[154:155]
	s_mov_b32 m0, s67
	ds_read_b128 v[190:193], v189 offset:16384
	ds_read_b128 v[194:197], v189 offset:17408
	ds_read_b128 v[198:201], v189 offset:18432
	ds_read_b128 v[202:205], v189 offset:19456
	ds_read_b128 v[206:209], v189 offset:20480
	ds_read_b128 v[210:213], v189 offset:21504
	ds_read_b128 v[214:217], v189 offset:22528
	ds_read_b128 v[218:221], v189 offset:23552
	global_load_lds_dwordx4 v[166:167], off
	s_add_i32 m0, s67, 0x2000
	s_add_u32 s68, s34, 0x40000
	v_lshl_add_u64 v[176:177], s[34:35], 0, v[150:151]
	s_addc_u32 s69, s35, 0
	s_add_i32 s67, s70, s48
	global_load_lds_dwordx4 v[176:177], off
	v_lshl_add_u64 v[222:223], s[68:69], 0, v[154:155]
	s_mov_b32 m0, s67
	v_lshl_add_u64 v[224:225], s[38:39], 0, v[152:153]
	global_load_lds_dwordx4 v[222:223], off
	v_lshl_add_u64 v[222:223], s[68:69], 0, v[150:151]
	s_add_i32 m0, s67, 0x2000
	s_nop 0
	global_load_lds_dwordx4 v[222:223], off
	v_lshl_add_u64 v[222:223], s[38:39], 0, v[156:157]
	s_mov_b32 m0, s49
	s_nop 0
	global_load_lds_dwordx4 v[222:223], off
	s_mov_b32 m0, s50
	s_nop 0
	global_load_lds_dwordx4 v[224:225], off
	s_waitcnt vmcnt(8)
	s_waitcnt lgkmcnt(0)
	s_barrier
	s_waitcnt lgkmcnt(0)
	v_mfma_f32_16x16x32_bf16 v[62:65], v[130:133], v[190:193], v[62:65]
	v_mfma_f32_16x16x32_bf16 v[58:61], v[138:141], v[190:193], v[58:61]
	v_mfma_f32_16x16x32_bf16 v[54:57], v[130:133], v[198:201], v[54:57]
	v_mfma_f32_16x16x32_bf16 v[46:49], v[138:141], v[198:201], v[46:49]
	v_mfma_f32_16x16x32_bf16 v[38:41], v[130:133], v[206:209], v[38:41]
	v_mfma_f32_16x16x32_bf16 v[30:33], v[138:141], v[206:209], v[30:33]
	v_mfma_f32_16x16x32_bf16 v[22:25], v[130:133], v[214:217], v[22:25]
	v_mfma_f32_16x16x32_bf16 v[14:17], v[138:141], v[214:217], v[14:17]
	v_mfma_f32_16x16x32_bf16 v[62:65], v[134:137], v[194:197], v[62:65]
	v_mfma_f32_16x16x32_bf16 v[58:61], v[142:145], v[194:197], v[58:61]
	v_mfma_f32_16x16x32_bf16 v[54:57], v[134:137], v[202:205], v[54:57]
	v_mfma_f32_16x16x32_bf16 v[46:49], v[142:145], v[202:205], v[46:49]
	v_mfma_f32_16x16x32_bf16 v[38:41], v[134:137], v[210:213], v[38:41]
	v_mfma_f32_16x16x32_bf16 v[30:33], v[142:145], v[210:213], v[30:33]
	v_mfma_f32_16x16x32_bf16 v[22:25], v[134:137], v[218:221], v[22:25]
	v_mfma_f32_16x16x32_bf16 v[14:17], v[142:145], v[218:221], v[14:17]
	v_mfma_f32_16x16x32_bf16 v[50:53], v[146:149], v[190:193], v[50:53]
	v_mfma_f32_16x16x32_bf16 v[42:45], v[172:175], v[190:193], v[42:45]
	v_mfma_f32_16x16x32_bf16 v[34:37], v[146:149], v[198:201], v[34:37]
	v_mfma_f32_16x16x32_bf16 v[26:29], v[172:175], v[198:201], v[26:29]
	v_mfma_f32_16x16x32_bf16 v[18:21], v[146:149], v[206:209], v[18:21]
	v_mfma_f32_16x16x32_bf16 v[10:13], v[172:175], v[206:209], v[10:13]
	v_mfma_f32_16x16x32_bf16 v[6:9], v[146:149], v[214:217], v[6:9]
	v_mfma_f32_16x16x32_bf16 v[2:5], v[172:175], v[214:217], v[2:5]
	v_mfma_f32_16x16x32_bf16 v[50:53], v[162:165], v[194:197], v[50:53]
	v_mfma_f32_16x16x32_bf16 v[42:45], v[184:187], v[194:197], v[42:45]
	v_mfma_f32_16x16x32_bf16 v[34:37], v[162:165], v[202:205], v[34:37]
	v_mfma_f32_16x16x32_bf16 v[26:29], v[184:187], v[202:205], v[26:29]
	v_mfma_f32_16x16x32_bf16 v[18:21], v[162:165], v[210:213], v[18:21]
	v_mfma_f32_16x16x32_bf16 v[10:13], v[184:187], v[210:213], v[10:13]
	v_mfma_f32_16x16x32_bf16 v[6:9], v[162:165], v[218:221], v[6:9]
	v_mfma_f32_16x16x32_bf16 v[2:5], v[184:187], v[218:221], v[2:5]
	s_barrier
	s_add_i32 s67, 0, 0x18000
	s_add_i32 s68, 0, 0x1c000
	v_add_u32_e32 v142, s67, v171
	v_add_u32_e32 v168, s68, v171
	ds_read_b128 v[130:133], v142
	ds_read_b128 v[134:137], v142 offset:1024
	ds_read_b128 v[138:141], v142 offset:2048
	ds_read_b128 v[142:145], v142 offset:3072
	ds_read_b128 v[146:149], v168
	ds_read_b128 v[162:165], v168 offset:1024
	ds_read_b128 v[172:175], v168 offset:2048
	ds_read_b128 v[184:187], v168 offset:3072
	s_add_u32 s38, s38, 0x40000
	s_addc_u32 s39, s39, 0
	s_mov_b32 m0, s51
	v_lshl_add_u64 v[226:227], s[38:39], 0, v[156:157]
	ds_read_b128 v[190:193], v189 offset:32768
	ds_read_b128 v[194:197], v189 offset:33792
	ds_read_b128 v[198:201], v189 offset:34816
	ds_read_b128 v[202:205], v189 offset:35840
	ds_read_b128 v[206:209], v189 offset:36864
	ds_read_b128 v[210:213], v189 offset:37888
	ds_read_b128 v[214:217], v189 offset:38912
	ds_read_b128 v[218:221], v189 offset:39936
	global_load_lds_dwordx4 v[226:227], off
	v_lshl_add_u64 v[226:227], s[38:39], 0, v[152:153]
	s_mov_b32 m0, s52
	s_nop 0
	global_load_lds_dwordx4 v[226:227], off
	s_waitcnt vmcnt(8)
	s_waitcnt lgkmcnt(0)
	s_barrier
	s_waitcnt lgkmcnt(0)
	v_mfma_f32_16x16x32_bf16 v[126:129], v[130:133], v[190:193], v[126:129]
	v_mfma_f32_16x16x32_bf16 v[122:125], v[138:141], v[190:193], v[122:125]
	v_mfma_f32_16x16x32_bf16 v[118:121], v[130:133], v[198:201], v[118:121]
	v_mfma_f32_16x16x32_bf16 v[110:113], v[138:141], v[198:201], v[110:113]
	v_mfma_f32_16x16x32_bf16 v[102:105], v[130:133], v[206:209], v[102:105]
	v_mfma_f32_16x16x32_bf16 v[94:97], v[138:141], v[206:209], v[94:97]
	v_mfma_f32_16x16x32_bf16 v[86:89], v[130:133], v[214:217], v[86:89]
	v_mfma_f32_16x16x32_bf16 v[78:81], v[138:141], v[214:217], v[78:81]
	v_mfma_f32_16x16x32_bf16 v[126:129], v[134:137], v[194:197], v[126:129]
	v_mfma_f32_16x16x32_bf16 v[122:125], v[142:145], v[194:197], v[122:125]
	v_mfma_f32_16x16x32_bf16 v[118:121], v[134:137], v[202:205], v[118:121]
	v_mfma_f32_16x16x32_bf16 v[110:113], v[142:145], v[202:205], v[110:113]
	v_mfma_f32_16x16x32_bf16 v[102:105], v[134:137], v[210:213], v[102:105]
	v_mfma_f32_16x16x32_bf16 v[94:97], v[142:145], v[210:213], v[94:97]
	v_mfma_f32_16x16x32_bf16 v[86:89], v[134:137], v[218:221], v[86:89]
	v_mfma_f32_16x16x32_bf16 v[78:81], v[142:145], v[218:221], v[78:81]
	v_mfma_f32_16x16x32_bf16 v[114:117], v[146:149], v[190:193], v[114:117]
	v_mfma_f32_16x16x32_bf16 v[106:109], v[172:175], v[190:193], v[106:109]
	v_mfma_f32_16x16x32_bf16 v[98:101], v[146:149], v[198:201], v[98:101]
	v_mfma_f32_16x16x32_bf16 v[90:93], v[172:175], v[198:201], v[90:93]
	v_mfma_f32_16x16x32_bf16 v[82:85], v[146:149], v[206:209], v[82:85]
	v_mfma_f32_16x16x32_bf16 v[74:77], v[172:175], v[206:209], v[74:77]
	v_mfma_f32_16x16x32_bf16 v[70:73], v[146:149], v[214:217], v[70:73]
	v_mfma_f32_16x16x32_bf16 v[66:69], v[172:175], v[214:217], v[66:69]
	v_mfma_f32_16x16x32_bf16 v[114:117], v[162:165], v[194:197], v[114:117]
	v_mfma_f32_16x16x32_bf16 v[106:109], v[184:187], v[194:197], v[106:109]
	v_mfma_f32_16x16x32_bf16 v[98:101], v[162:165], v[202:205], v[98:101]
	v_mfma_f32_16x16x32_bf16 v[90:93], v[184:187], v[202:205], v[90:93]
	v_mfma_f32_16x16x32_bf16 v[82:85], v[162:165], v[210:213], v[82:85]
	v_mfma_f32_16x16x32_bf16 v[74:77], v[184:187], v[210:213], v[74:77]
	v_mfma_f32_16x16x32_bf16 v[70:73], v[162:165], v[218:221], v[70:73]
	v_mfma_f32_16x16x32_bf16 v[66:69], v[184:187], v[218:221], v[66:69]
	s_barrier
	s_add_i32 s38, s67, s48
	v_lshl_add_u64 v[166:167], v[166:167], 0, s[72:73]
	s_mov_b32 m0, s38
	ds_read_b128 v[190:193], v189 offset:49152
	ds_read_b128 v[194:197], v189 offset:50176
	ds_read_b128 v[198:201], v189 offset:51200
	ds_read_b128 v[202:205], v189 offset:52224
	ds_read_b128 v[206:209], v189 offset:53248
	ds_read_b128 v[210:213], v189 offset:54272
	ds_read_b128 v[214:217], v189 offset:55296
	ds_read_b128 v[218:221], v189 offset:56320
	global_load_lds_dwordx4 v[166:167], off
	s_add_i32 m0, s38, 0x2000
	s_add_u32 s34, s34, 0x40080
	v_lshl_add_u64 v[166:167], v[176:177], 0, s[72:73]
	s_addc_u32 s35, s35, 0
	s_add_i32 s38, s68, s48
	global_load_lds_dwordx4 v[166:167], off
	v_lshl_add_u64 v[166:167], s[34:35], 0, v[154:155]
	s_mov_b32 m0, s38
	s_nop 0
	global_load_lds_dwordx4 v[166:167], off
	v_lshl_add_u64 v[166:167], s[34:35], 0, v[150:151]
	s_add_i32 m0, s38, 0x2000
	s_nop 0
	global_load_lds_dwordx4 v[166:167], off
	v_lshl_add_u64 v[166:167], v[222:223], 0, s[72:73]
	s_mov_b32 m0, s58
	s_nop 0
	global_load_lds_dwordx4 v[166:167], off
	v_lshl_add_u64 v[166:167], v[224:225], 0, s[72:73]
	s_mov_b32 m0, s59
	s_nop 0
	global_load_lds_dwordx4 v[166:167], off
	s_waitcnt vmcnt(8)
	s_waitcnt lgkmcnt(0)
	s_barrier
	s_waitcnt lgkmcnt(0)
	v_mfma_f32_16x16x32_bf16 v[62:65], v[130:133], v[190:193], v[62:65]
	v_mfma_f32_16x16x32_bf16 v[58:61], v[138:141], v[190:193], v[58:61]
	v_mfma_f32_16x16x32_bf16 v[54:57], v[130:133], v[198:201], v[54:57]
	v_mfma_f32_16x16x32_bf16 v[46:49], v[138:141], v[198:201], v[46:49]
	v_mfma_f32_16x16x32_bf16 v[38:41], v[130:133], v[206:209], v[38:41]
	v_mfma_f32_16x16x32_bf16 v[30:33], v[138:141], v[206:209], v[30:33]
	v_mfma_f32_16x16x32_bf16 v[22:25], v[130:133], v[214:217], v[22:25]
	v_mfma_f32_16x16x32_bf16 v[14:17], v[138:141], v[214:217], v[14:17]
	v_mfma_f32_16x16x32_bf16 v[62:65], v[134:137], v[194:197], v[62:65]
	v_mfma_f32_16x16x32_bf16 v[58:61], v[142:145], v[194:197], v[58:61]
	v_mfma_f32_16x16x32_bf16 v[54:57], v[134:137], v[202:205], v[54:57]
	v_mfma_f32_16x16x32_bf16 v[46:49], v[142:145], v[202:205], v[46:49]
	v_mfma_f32_16x16x32_bf16 v[38:41], v[134:137], v[210:213], v[38:41]
	v_mfma_f32_16x16x32_bf16 v[30:33], v[142:145], v[210:213], v[30:33]
	v_mfma_f32_16x16x32_bf16 v[22:25], v[134:137], v[218:221], v[22:25]
	v_mfma_f32_16x16x32_bf16 v[14:17], v[142:145], v[218:221], v[14:17]
	v_mfma_f32_16x16x32_bf16 v[50:53], v[146:149], v[190:193], v[50:53]
	v_mfma_f32_16x16x32_bf16 v[42:45], v[172:175], v[190:193], v[42:45]
	v_mfma_f32_16x16x32_bf16 v[34:37], v[146:149], v[198:201], v[34:37]
	v_mfma_f32_16x16x32_bf16 v[26:29], v[172:175], v[198:201], v[26:29]
	v_mfma_f32_16x16x32_bf16 v[18:21], v[146:149], v[206:209], v[18:21]
	v_mfma_f32_16x16x32_bf16 v[10:13], v[172:175], v[206:209], v[10:13]
	v_mfma_f32_16x16x32_bf16 v[6:9], v[146:149], v[214:217], v[6:9]
	v_mfma_f32_16x16x32_bf16 v[2:5], v[172:175], v[214:217], v[2:5]
	v_mfma_f32_16x16x32_bf16 v[50:53], v[162:165], v[194:197], v[50:53]
	v_mfma_f32_16x16x32_bf16 v[42:45], v[184:187], v[194:197], v[42:45]
	v_mfma_f32_16x16x32_bf16 v[34:37], v[162:165], v[202:205], v[34:37]
	v_mfma_f32_16x16x32_bf16 v[26:29], v[184:187], v[202:205], v[26:29]
	v_mfma_f32_16x16x32_bf16 v[18:21], v[162:165], v[210:213], v[18:21]
	v_mfma_f32_16x16x32_bf16 v[10:13], v[184:187], v[210:213], v[10:13]
	v_mfma_f32_16x16x32_bf16 v[6:9], v[162:165], v[218:221], v[6:9]
	v_mfma_f32_16x16x32_bf16 v[2:5], v[184:187], v[218:221], v[2:5]
	s_barrier
	s_add_i32 s66, s66, 2
	s_add_u32 s6, s6, 0x100
	s_addc_u32 s7, s7, 0
	s_add_u32 s64, s64, 0x100
	s_addc_u32 s65, s65, 0
	s_cmp_gt_u32 s66, 13
	s_cbranch_scc0 .LBB0_183
	s_and_b64 vcc, exec, s[14:15]
	s_movk_i32 s64, 0x41
	s_movk_i32 s65, 0x210
	s_movk_i32 s66, 0x160
	s_cbranch_vccz .LBB0_186
	s_barrier

.LBB0_429:
	s_add_u32 s34, s28, 0xfffc0080
	s_addc_u32 s35, s29, -1
	s_add_i32 s71, 0, 0x10000
	s_cmp_eq_u32 s70, 12
	s_cselect_b32 s39, s17, s35
	s_cselect_b32 s38, s62, s34
	s_cselect_b32 s35, s15, s69
	s_cselect_b32 s34, s67, s68
	s_add_i32 s76, 0, 0x14000
	v_add_u32_e32 v106, s71, v220
	v_add_u32_e32 v158, s76, v220
	ds_read_b128 v[90:93], v106
	ds_read_b128 v[94:97], v106 offset:1024
	ds_read_b128 v[98:101], v106 offset:2048
	ds_read_b128 v[106:109], v106 offset:3072
	ds_read_b128 v[146:149], v158
	ds_read_b128 v[150:153], v158 offset:1024
	ds_read_b128 v[154:157], v158 offset:2048
	ds_read_b128 v[158:161], v158 offset:3072
	v_lshl_add_u64 v[214:215], s[28:29], 0, v[190:191]
	s_add_i32 m0, s50, 0xc000
	ds_read_b128 v[162:165], v221
	ds_read_b128 v[166:169], v221 offset:1024
	ds_read_b128 v[184:187], v221 offset:2048
	ds_read_b128 v[194:197], v221 offset:3072
	ds_read_b128 v[198:201], v221 offset:4096
	ds_read_b128 v[202:205], v221 offset:5120
	ds_read_b128 v[206:209], v221 offset:6144
	ds_read_b128 v[210:213], v221 offset:7168
	global_load_lds_dwordx4 v[214:215], off
	v_lshl_add_u64 v[214:215], s[28:29], 0, v[192:193]
	s_add_i32 m0, s50, 0xe000
	s_nop 0
	global_load_lds_dwordx4 v[214:215], off
	s_waitcnt vmcnt(8)
	s_waitcnt lgkmcnt(0)
	s_barrier
	s_waitcnt lgkmcnt(0)
	v_mfma_f32_16x16x32_bf16 v[142:145], v[90:93], v[162:165], v[142:145]
	v_mfma_f32_16x16x32_bf16 v[138:141], v[98:101], v[162:165], v[138:141]
	v_mfma_f32_16x16x32_bf16 v[126:129], v[90:93], v[184:187], v[126:129]
	v_mfma_f32_16x16x32_bf16 v[122:125], v[98:101], v[184:187], v[122:125]
	v_mfma_f32_16x16x32_bf16 v[110:113], v[90:93], v[198:201], v[110:113]
	v_mfma_f32_16x16x32_bf16 v[102:105], v[98:101], v[198:201], v[102:105]
	v_mfma_f32_16x16x32_bf16 v[78:81], v[90:93], v[206:209], v[78:81]
	v_mfma_f32_16x16x32_bf16 v[74:77], v[98:101], v[206:209], v[74:77]
	v_mfma_f32_16x16x32_bf16 v[142:145], v[94:97], v[166:169], v[142:145]
	v_mfma_f32_16x16x32_bf16 v[138:141], v[106:109], v[166:169], v[138:141]
	v_mfma_f32_16x16x32_bf16 v[126:129], v[94:97], v[194:197], v[126:129]
	v_mfma_f32_16x16x32_bf16 v[122:125], v[106:109], v[194:197], v[122:125]
	v_mfma_f32_16x16x32_bf16 v[110:113], v[94:97], v[202:205], v[110:113]
	v_mfma_f32_16x16x32_bf16 v[102:105], v[106:109], v[202:205], v[102:105]
	v_mfma_f32_16x16x32_bf16 v[78:81], v[94:97], v[210:213], v[78:81]
	v_mfma_f32_16x16x32_bf16 v[74:77], v[106:109], v[210:213], v[74:77]
	v_mfma_f32_16x16x32_bf16 v[134:137], v[146:149], v[162:165], v[134:137]
	v_mfma_f32_16x16x32_bf16 v[130:133], v[154:157], v[162:165], v[130:133]
	v_mfma_f32_16x16x32_bf16 v[118:121], v[146:149], v[184:187], v[118:121]
	v_mfma_f32_16x16x32_bf16 v[114:117], v[154:157], v[184:187], v[114:117]
	v_mfma_f32_16x16x32_bf16 v[86:89], v[146:149], v[198:201], v[86:89]
	v_mfma_f32_16x16x32_bf16 v[82:85], v[154:157], v[198:201], v[82:85]
	v_mfma_f32_16x16x32_bf16 v[70:73], v[146:149], v[206:209], v[70:73]
	v_mfma_f32_16x16x32_bf16 v[66:69], v[154:157], v[206:209], v[66:69]
	v_mfma_f32_16x16x32_bf16 v[134:137], v[150:153], v[166:169], v[134:137]
	v_mfma_f32_16x16x32_bf16 v[130:133], v[158:161], v[166:169], v[130:133]
	v_mfma_f32_16x16x32_bf16 v[118:121], v[150:153], v[194:197], v[118:121]
	v_mfma_f32_16x16x32_bf16 v[114:117], v[158:161], v[194:197], v[114:117]
	v_mfma_f32_16x16x32_bf16 v[86:89], v[150:153], v[202:205], v[86:89]
	v_mfma_f32_16x16x32_bf16 v[82:85], v[158:161], v[202:205], v[82:85]
	v_mfma_f32_16x16x32_bf16 v[70:73], v[150:153], v[210:213], v[70:73]
	v_mfma_f32_16x16x32_bf16 v[66:69], v[158:161], v[210:213], v[66:69]
	s_barrier
	s_add_i32 s71, s71, s49
	v_lshl_add_u64 v[214:215], s[34:35], 0, v[174:175]
	s_mov_b32 m0, s71
	ds_read_b128 v[162:165], v221 offset:16384
	ds_read_b128 v[166:169], v221 offset:17408
	ds_read_b128 v[184:187], v221 offset:18432
	ds_read_b128 v[194:197], v221 offset:19456
	ds_read_b128 v[198:201], v221 offset:20480
	ds_read_b128 v[202:205], v221 offset:21504
	ds_read_b128 v[206:209], v221 offset:22528
	ds_read_b128 v[210:213], v221 offset:23552
	global_load_lds_dwordx4 v[214:215], off
	s_add_i32 m0, s71, 0x2000
	s_add_u32 s74, s34, 0x40000
	v_lshl_add_u64 v[216:217], s[34:35], 0, v[170:171]
	s_addc_u32 s75, s35, 0
	s_add_i32 s71, s76, s49
	global_load_lds_dwordx4 v[216:217], off
	v_lshl_add_u64 v[218:219], s[74:75], 0, v[174:175]
	s_mov_b32 m0, s71
	v_lshl_add_u64 v[222:223], s[38:39], 0, v[172:173]
	global_load_lds_dwordx4 v[218:219], off
	v_lshl_add_u64 v[218:219], s[74:75], 0, v[170:171]
	s_add_i32 m0, s71, 0x2000
	s_nop 0
	global_load_lds_dwordx4 v[218:219], off
	v_lshl_add_u64 v[218:219], s[38:39], 0, v[176:177]
	s_mov_b32 m0, s50
	s_nop 0
	global_load_lds_dwordx4 v[218:219], off
	s_mov_b32 m0, s51
	s_nop 0
	global_load_lds_dwordx4 v[222:223], off
	s_waitcnt vmcnt(8)
	s_waitcnt lgkmcnt(0)
	s_barrier
	s_waitcnt lgkmcnt(0)
	v_mfma_f32_16x16x32_bf16 v[62:65], v[90:93], v[162:165], v[62:65]
	v_mfma_f32_16x16x32_bf16 v[58:61], v[98:101], v[162:165], v[58:61]
	v_mfma_f32_16x16x32_bf16 v[46:49], v[90:93], v[184:187], v[46:49]
	v_mfma_f32_16x16x32_bf16 v[42:45], v[98:101], v[184:187], v[42:45]
	v_mfma_f32_16x16x32_bf16 v[30:33], v[90:93], v[198:201], v[30:33]
	v_mfma_f32_16x16x32_bf16 v[26:29], v[98:101], v[198:201], v[26:29]
	v_mfma_f32_16x16x32_bf16 v[14:17], v[90:93], v[206:209], v[14:17]
	v_mfma_f32_16x16x32_bf16 v[10:13], v[98:101], v[206:209], v[10:13]
	v_mfma_f32_16x16x32_bf16 v[62:65], v[94:97], v[166:169], v[62:65]
	v_mfma_f32_16x16x32_bf16 v[58:61], v[106:109], v[166:169], v[58:61]
	v_mfma_f32_16x16x32_bf16 v[46:49], v[94:97], v[194:197], v[46:49]
	v_mfma_f32_16x16x32_bf16 v[42:45], v[106:109], v[194:197], v[42:45]
	v_mfma_f32_16x16x32_bf16 v[30:33], v[94:97], v[202:205], v[30:33]
	v_mfma_f32_16x16x32_bf16 v[26:29], v[106:109], v[202:205], v[26:29]
	v_mfma_f32_16x16x32_bf16 v[14:17], v[94:97], v[210:213], v[14:17]
	v_mfma_f32_16x16x32_bf16 v[10:13], v[106:109], v[210:213], v[10:13]
	v_mfma_f32_16x16x32_bf16 v[54:57], v[146:149], v[162:165], v[54:57]
	v_mfma_f32_16x16x32_bf16 v[50:53], v[154:157], v[162:165], v[50:53]
	v_mfma_f32_16x16x32_bf16 v[38:41], v[146:149], v[184:187], v[38:41]
	v_mfma_f32_16x16x32_bf16 v[34:37], v[154:157], v[184:187], v[34:37]
	v_mfma_f32_16x16x32_bf16 v[22:25], v[146:149], v[198:201], v[22:25]
	v_mfma_f32_16x16x32_bf16 v[18:21], v[154:157], v[198:201], v[18:21]
	v_mfma_f32_16x16x32_bf16 v[6:9], v[146:149], v[206:209], v[6:9]
	v_mfma_f32_16x16x32_bf16 v[2:5], v[154:157], v[206:209], v[2:5]
	v_mfma_f32_16x16x32_bf16 v[54:57], v[150:153], v[166:169], v[54:57]
	v_mfma_f32_16x16x32_bf16 v[50:53], v[158:161], v[166:169], v[50:53]
	v_mfma_f32_16x16x32_bf16 v[38:41], v[150:153], v[194:197], v[38:41]
	v_mfma_f32_16x16x32_bf16 v[34:37], v[158:161], v[194:197], v[34:37]
	v_mfma_f32_16x16x32_bf16 v[22:25], v[150:153], v[202:205], v[22:25]
	v_mfma_f32_16x16x32_bf16 v[18:21], v[158:161], v[202:205], v[18:21]
	v_mfma_f32_16x16x32_bf16 v[6:9], v[150:153], v[210:213], v[6:9]
	v_mfma_f32_16x16x32_bf16 v[2:5], v[158:161], v[210:213], v[2:5]
	s_barrier
	s_add_i32 s71, 0, 0x18000
	s_add_i32 s74, 0, 0x1c000
	v_add_u32_e32 v106, s71, v220
	v_add_u32_e32 v158, s74, v220
	ds_read_b128 v[90:93], v106
	ds_read_b128 v[94:97], v106 offset:1024
	ds_read_b128 v[98:101], v106 offset:2048
	ds_read_b128 v[106:109], v106 offset:3072
	ds_read_b128 v[146:149], v158
	ds_read_b128 v[150:153], v158 offset:1024
	ds_read_b128 v[154:157], v158 offset:2048
	ds_read_b128 v[158:161], v158 offset:3072
	s_add_u32 s38, s38, 0x40000
	s_addc_u32 s39, s39, 0
	s_mov_b32 m0, s52
	v_lshl_add_u64 v[224:225], s[38:39], 0, v[176:177]
	ds_read_b128 v[162:165], v221 offset:32768
	ds_read_b128 v[166:169], v221 offset:33792
	ds_read_b128 v[184:187], v221 offset:34816
	ds_read_b128 v[194:197], v221 offset:35840
	ds_read_b128 v[198:201], v221 offset:36864
	ds_read_b128 v[202:205], v221 offset:37888
	ds_read_b128 v[206:209], v221 offset:38912
	ds_read_b128 v[210:213], v221 offset:39936
	global_load_lds_dwordx4 v[224:225], off
	v_lshl_add_u64 v[224:225], s[38:39], 0, v[172:173]
	s_mov_b32 m0, s53
	s_nop 0
	global_load_lds_dwordx4 v[224:225], off
	s_waitcnt vmcnt(8)
	s_waitcnt lgkmcnt(0)
	s_barrier
	s_waitcnt lgkmcnt(0)
	v_mfma_f32_16x16x32_bf16 v[142:145], v[90:93], v[162:165], v[142:145]
	v_mfma_f32_16x16x32_bf16 v[138:141], v[98:101], v[162:165], v[138:141]
	v_mfma_f32_16x16x32_bf16 v[126:129], v[90:93], v[184:187], v[126:129]
	v_mfma_f32_16x16x32_bf16 v[122:125], v[98:101], v[184:187], v[122:125]
	v_mfma_f32_16x16x32_bf16 v[110:113], v[90:93], v[198:201], v[110:113]
	v_mfma_f32_16x16x32_bf16 v[102:105], v[98:101], v[198:201], v[102:105]
	v_mfma_f32_16x16x32_bf16 v[78:81], v[90:93], v[206:209], v[78:81]
	v_mfma_f32_16x16x32_bf16 v[74:77], v[98:101], v[206:209], v[74:77]
	v_mfma_f32_16x16x32_bf16 v[142:145], v[94:97], v[166:169], v[142:145]
	v_mfma_f32_16x16x32_bf16 v[138:141], v[106:109], v[166:169], v[138:141]
	v_mfma_f32_16x16x32_bf16 v[126:129], v[94:97], v[194:197], v[126:129]
	v_mfma_f32_16x16x32_bf16 v[122:125], v[106:109], v[194:197], v[122:125]
	v_mfma_f32_16x16x32_bf16 v[110:113], v[94:97], v[202:205], v[110:113]
	v_mfma_f32_16x16x32_bf16 v[102:105], v[106:109], v[202:205], v[102:105]
	v_mfma_f32_16x16x32_bf16 v[78:81], v[94:97], v[210:213], v[78:81]
	v_mfma_f32_16x16x32_bf16 v[74:77], v[106:109], v[210:213], v[74:77]
	v_mfma_f32_16x16x32_bf16 v[134:137], v[146:149], v[162:165], v[134:137]
	v_mfma_f32_16x16x32_bf16 v[130:133], v[154:157], v[162:165], v[130:133]
	v_mfma_f32_16x16x32_bf16 v[118:121], v[146:149], v[184:187], v[118:121]
	v_mfma_f32_16x16x32_bf16 v[114:117], v[154:157], v[184:187], v[114:117]
	v_mfma_f32_16x16x32_bf16 v[86:89], v[146:149], v[198:201], v[86:89]
	v_mfma_f32_16x16x32_bf16 v[82:85], v[154:157], v[198:201], v[82:85]
	v_mfma_f32_16x16x32_bf16 v[70:73], v[146:149], v[206:209], v[70:73]
	v_mfma_f32_16x16x32_bf16 v[66:69], v[154:157], v[206:209], v[66:69]
	v_mfma_f32_16x16x32_bf16 v[134:137], v[150:153], v[166:169], v[134:137]
	v_mfma_f32_16x16x32_bf16 v[130:133], v[158:161], v[166:169], v[130:133]
	v_mfma_f32_16x16x32_bf16 v[118:121], v[150:153], v[194:197], v[118:121]
	v_mfma_f32_16x16x32_bf16 v[114:117], v[158:161], v[194:197], v[114:117]
	v_mfma_f32_16x16x32_bf16 v[86:89], v[150:153], v[202:205], v[86:89]
	v_mfma_f32_16x16x32_bf16 v[82:85], v[158:161], v[202:205], v[82:85]
	v_mfma_f32_16x16x32_bf16 v[70:73], v[150:153], v[210:213], v[70:73]
	v_mfma_f32_16x16x32_bf16 v[66:69], v[158:161], v[210:213], v[66:69]
	s_barrier
	s_add_i32 s38, s71, s49
	v_lshl_add_u64 v[214:215], v[214:215], 0, s[72:73]
	s_mov_b32 m0, s38
	ds_read_b128 v[162:165], v221 offset:49152
	ds_read_b128 v[166:169], v221 offset:50176
	ds_read_b128 v[184:187], v221 offset:51200
	ds_read_b128 v[194:197], v221 offset:52224
	ds_read_b128 v[198:201], v221 offset:53248
	ds_read_b128 v[202:205], v221 offset:54272
	ds_read_b128 v[206:209], v221 offset:55296
	ds_read_b128 v[210:213], v221 offset:56320
	global_load_lds_dwordx4 v[214:215], off
	s_add_i32 m0, s38, 0x2000
	s_add_u32 s34, s34, 0x40080
	v_lshl_add_u64 v[214:215], v[216:217], 0, s[72:73]
	s_addc_u32 s35, s35, 0
	s_add_i32 s38, s74, s49
	global_load_lds_dwordx4 v[214:215], off
	v_lshl_add_u64 v[214:215], s[34:35], 0, v[174:175]
	s_mov_b32 m0, s38
	s_nop 0
	global_load_lds_dwordx4 v[214:215], off
	v_lshl_add_u64 v[214:215], s[34:35], 0, v[170:171]
	s_add_i32 m0, s38, 0x2000
	s_nop 0
	global_load_lds_dwordx4 v[214:215], off
	v_lshl_add_u64 v[214:215], v[218:219], 0, s[72:73]
	s_mov_b32 m0, s64
	s_nop 0
	global_load_lds_dwordx4 v[214:215], off
	v_lshl_add_u64 v[214:215], v[222:223], 0, s[72:73]
	s_mov_b32 m0, s65
	s_nop 0
	global_load_lds_dwordx4 v[214:215], off
	s_waitcnt vmcnt(8)
	s_waitcnt lgkmcnt(0)
	s_barrier
	s_waitcnt lgkmcnt(0)
	v_mfma_f32_16x16x32_bf16 v[62:65], v[90:93], v[162:165], v[62:65]
	v_mfma_f32_16x16x32_bf16 v[58:61], v[98:101], v[162:165], v[58:61]
	v_mfma_f32_16x16x32_bf16 v[46:49], v[90:93], v[184:187], v[46:49]
	v_mfma_f32_16x16x32_bf16 v[42:45], v[98:101], v[184:187], v[42:45]
	v_mfma_f32_16x16x32_bf16 v[30:33], v[90:93], v[198:201], v[30:33]
	v_mfma_f32_16x16x32_bf16 v[26:29], v[98:101], v[198:201], v[26:29]
	v_mfma_f32_16x16x32_bf16 v[14:17], v[90:93], v[206:209], v[14:17]
	v_mfma_f32_16x16x32_bf16 v[10:13], v[98:101], v[206:209], v[10:13]
	v_mfma_f32_16x16x32_bf16 v[62:65], v[94:97], v[166:169], v[62:65]
	v_mfma_f32_16x16x32_bf16 v[58:61], v[106:109], v[166:169], v[58:61]
	v_mfma_f32_16x16x32_bf16 v[46:49], v[94:97], v[194:197], v[46:49]
	v_mfma_f32_16x16x32_bf16 v[42:45], v[106:109], v[194:197], v[42:45]
	v_mfma_f32_16x16x32_bf16 v[30:33], v[94:97], v[202:205], v[30:33]
	v_mfma_f32_16x16x32_bf16 v[26:29], v[106:109], v[202:205], v[26:29]
	v_mfma_f32_16x16x32_bf16 v[14:17], v[94:97], v[210:213], v[14:17]
	v_mfma_f32_16x16x32_bf16 v[10:13], v[106:109], v[210:213], v[10:13]
	v_mfma_f32_16x16x32_bf16 v[54:57], v[146:149], v[162:165], v[54:57]
	v_mfma_f32_16x16x32_bf16 v[50:53], v[154:157], v[162:165], v[50:53]
	v_mfma_f32_16x16x32_bf16 v[38:41], v[146:149], v[184:187], v[38:41]
	v_mfma_f32_16x16x32_bf16 v[34:37], v[154:157], v[184:187], v[34:37]
	v_mfma_f32_16x16x32_bf16 v[22:25], v[146:149], v[198:201], v[22:25]
	v_mfma_f32_16x16x32_bf16 v[18:21], v[154:157], v[198:201], v[18:21]
	v_mfma_f32_16x16x32_bf16 v[6:9], v[146:149], v[206:209], v[6:9]
	v_mfma_f32_16x16x32_bf16 v[2:5], v[154:157], v[206:209], v[2:5]
	v_mfma_f32_16x16x32_bf16 v[54:57], v[150:153], v[166:169], v[54:57]
	v_mfma_f32_16x16x32_bf16 v[50:53], v[158:161], v[166:169], v[50:53]
	v_mfma_f32_16x16x32_bf16 v[38:41], v[150:153], v[194:197], v[38:41]
	v_mfma_f32_16x16x32_bf16 v[34:37], v[158:161], v[194:197], v[34:37]
	v_mfma_f32_16x16x32_bf16 v[22:25], v[150:153], v[202:205], v[22:25]
	v_mfma_f32_16x16x32_bf16 v[18:21], v[158:161], v[202:205], v[18:21]
	v_mfma_f32_16x16x32_bf16 v[6:9], v[150:153], v[210:213], v[6:9]
	v_mfma_f32_16x16x32_bf16 v[2:5], v[158:161], v[210:213], v[2:5]
	s_barrier
	s_add_i32 s70, s70, 2
	s_add_u32 s28, s28, 0x100
	s_addc_u32 s29, s29, 0
	s_add_u32 s68, s68, 0x100
	s_addc_u32 s69, s69, 0
	s_cmp_gt_u32 s70, 13
	s_cbranch_scc0 .LBB0_429
	v_mov_b32_e32 v146, v1
	v_mov_b32_e32 v90, v189
	s_cmp_lt_i32 s19, 32
	s_mov_b64 s[28:29], 0
	s_cbranch_scc1 .LBB0_432
	s_sub_i32 s15, s19, 32
	s_lshr_b32 s15, s15, 2
	s_add_i32 s15, s15, 1
	s_mul_hi_u32 s29, s15, 0x1800
	s_mul_i32 s28, s15, 0x1800

.LBB0_520:
	s_add_u32 s10, s8, 0xfffc0080
	s_addc_u32 s11, s9, -1
	s_add_i32 s54, 0, 0x10000
	s_cmp_eq_u32 s23, 12
	s_cselect_b32 s13, s15, s11
	s_cselect_b32 s12, s16, s10
	s_cselect_b32 s11, s17, s22
	s_cselect_b32 s10, s19, s21
	s_add_i32 s61, 0, 0x14000
	v_add_u32_e32 v94, s54, v242
	v_add_u32_e32 v158, s61, v242
	ds_read_b128 v[82:85], v94
	ds_read_b128 v[86:89], v94 offset:1024
	ds_read_b128 v[90:93], v94 offset:2048
	ds_read_b128 v[94:97], v94 offset:3072
	ds_read_b128 v[146:149], v158
	ds_read_b128 v[150:153], v158 offset:1024
	ds_read_b128 v[154:157], v158 offset:2048
	ds_read_b128 v[158:161], v158 offset:3072
	v_lshl_add_u64 v[214:215], s[8:9], 0, v[190:191]
	s_add_i32 m0, s59, 0xc000
	ds_read_b128 v[162:165], v243
	ds_read_b128 v[166:169], v243 offset:1024
	ds_read_b128 v[184:187], v243 offset:2048
	ds_read_b128 v[194:197], v243 offset:3072
	ds_read_b128 v[198:201], v243 offset:4096
	ds_read_b128 v[202:205], v243 offset:5120
	ds_read_b128 v[206:209], v243 offset:6144
	ds_read_b128 v[210:213], v243 offset:7168
	global_load_lds_dwordx4 v[214:215], off
	v_lshl_add_u64 v[214:215], s[8:9], 0, v[192:193]
	s_add_i32 m0, s59, 0xe000
	s_nop 0
	global_load_lds_dwordx4 v[214:215], off
	s_waitcnt vmcnt(8)
	s_waitcnt lgkmcnt(0)
	s_barrier
	s_waitcnt lgkmcnt(0)
	v_mfma_f32_16x16x32_bf16 v[62:65], v[82:85], v[162:165], v[62:65]
	v_mfma_f32_16x16x32_bf16 v[58:61], v[90:93], v[162:165], v[58:61]
	v_mfma_f32_16x16x32_bf16 v[54:57], v[82:85], v[184:187], v[54:57]
	v_mfma_f32_16x16x32_bf16 v[50:53], v[90:93], v[184:187], v[50:53]
	v_mfma_f32_16x16x32_bf16 v[46:49], v[82:85], v[198:201], v[46:49]
	v_mfma_f32_16x16x32_bf16 v[42:45], v[90:93], v[198:201], v[42:45]
	v_mfma_f32_16x16x32_bf16 v[38:41], v[82:85], v[206:209], v[38:41]
	v_mfma_f32_16x16x32_bf16 v[34:37], v[90:93], v[206:209], v[34:37]
	v_mfma_f32_16x16x32_bf16 v[62:65], v[86:89], v[166:169], v[62:65]
	v_mfma_f32_16x16x32_bf16 v[58:61], v[94:97], v[166:169], v[58:61]
	v_mfma_f32_16x16x32_bf16 v[54:57], v[86:89], v[194:197], v[54:57]
	v_mfma_f32_16x16x32_bf16 v[50:53], v[94:97], v[194:197], v[50:53]
	v_mfma_f32_16x16x32_bf16 v[46:49], v[86:89], v[202:205], v[46:49]
	v_mfma_f32_16x16x32_bf16 v[42:45], v[94:97], v[202:205], v[42:45]
	v_mfma_f32_16x16x32_bf16 v[38:41], v[86:89], v[210:213], v[38:41]
	v_mfma_f32_16x16x32_bf16 v[34:37], v[94:97], v[210:213], v[34:37]
	v_mfma_f32_16x16x32_bf16 v[142:145], v[146:149], v[162:165], v[142:145]
	v_mfma_f32_16x16x32_bf16 v[138:141], v[154:157], v[162:165], v[138:141]
	v_mfma_f32_16x16x32_bf16 v[134:137], v[146:149], v[184:187], v[134:137]
	v_mfma_f32_16x16x32_bf16 v[130:133], v[154:157], v[184:187], v[130:133]
	v_mfma_f32_16x16x32_bf16 v[126:129], v[146:149], v[198:201], v[126:129]
	v_mfma_f32_16x16x32_bf16 v[122:125], v[154:157], v[198:201], v[122:125]
	v_mfma_f32_16x16x32_bf16 v[118:121], v[146:149], v[206:209], v[118:121]
	v_mfma_f32_16x16x32_bf16 v[114:117], v[154:157], v[206:209], v[114:117]
	v_mfma_f32_16x16x32_bf16 v[142:145], v[150:153], v[166:169], v[142:145]
	v_mfma_f32_16x16x32_bf16 v[138:141], v[158:161], v[166:169], v[138:141]
	v_mfma_f32_16x16x32_bf16 v[134:137], v[150:153], v[194:197], v[134:137]
	v_mfma_f32_16x16x32_bf16 v[130:133], v[158:161], v[194:197], v[130:133]
	v_mfma_f32_16x16x32_bf16 v[126:129], v[150:153], v[202:205], v[126:129]
	v_mfma_f32_16x16x32_bf16 v[122:125], v[158:161], v[202:205], v[122:125]
	v_mfma_f32_16x16x32_bf16 v[118:121], v[150:153], v[210:213], v[118:121]
	v_mfma_f32_16x16x32_bf16 v[114:117], v[158:161], v[210:213], v[114:117]
	s_barrier
	s_add_i32 s54, s54, s28
	v_lshl_add_u64 v[214:215], s[10:11], 0, v[174:175]
	s_mov_b32 m0, s54
	ds_read_b128 v[162:165], v243 offset:16384
	ds_read_b128 v[166:169], v243 offset:17408
	ds_read_b128 v[184:187], v243 offset:18432
	ds_read_b128 v[194:197], v243 offset:19456
	ds_read_b128 v[198:201], v243 offset:20480
	ds_read_b128 v[202:205], v243 offset:21504
	ds_read_b128 v[206:209], v243 offset:22528
	ds_read_b128 v[210:213], v243 offset:23552
	global_load_lds_dwordx4 v[214:215], off
	s_add_i32 m0, s54, 0x2000
	s_add_u32 vcc_lo, s10, 0x40000
	v_lshl_add_u64 v[216:217], s[10:11], 0, v[170:171]
	s_addc_u32 vcc_hi, s11, 0
	s_add_i32 s54, s61, s28
	global_load_lds_dwordx4 v[216:217], off
	v_lshl_add_u64 v[218:219], vcc, 0, v[174:175]
	s_mov_b32 m0, s54
	v_lshl_add_u64 v[220:221], s[12:13], 0, v[172:173]
	global_load_lds_dwordx4 v[218:219], off
	v_lshl_add_u64 v[218:219], vcc, 0, v[170:171]
	s_add_i32 m0, s54, 0x2000
	s_nop 0
	global_load_lds_dwordx4 v[218:219], off
	v_lshl_add_u64 v[218:219], s[12:13], 0, v[176:177]
	s_mov_b32 m0, s59
	s_nop 0
	global_load_lds_dwordx4 v[218:219], off
	s_mov_b32 m0, s62
	s_nop 0
	global_load_lds_dwordx4 v[220:221], off
	s_waitcnt vmcnt(8)
	s_waitcnt lgkmcnt(0)
	s_barrier
	s_waitcnt lgkmcnt(0)
	v_mfma_f32_16x16x32_bf16 v[30:33], v[82:85], v[162:165], v[30:33]
	v_mfma_f32_16x16x32_bf16 v[26:29], v[90:93], v[162:165], v[26:29]
	v_mfma_f32_16x16x32_bf16 v[22:25], v[82:85], v[184:187], v[22:25]
	v_mfma_f32_16x16x32_bf16 v[18:21], v[90:93], v[184:187], v[18:21]
	v_mfma_f32_16x16x32_bf16 v[14:17], v[82:85], v[198:201], v[14:17]
	v_mfma_f32_16x16x32_bf16 v[10:13], v[90:93], v[198:201], v[10:13]
	v_mfma_f32_16x16x32_bf16 v[6:9], v[82:85], v[206:209], v[6:9]
	v_mfma_f32_16x16x32_bf16 v[2:5], v[90:93], v[206:209], v[2:5]
	v_mfma_f32_16x16x32_bf16 v[30:33], v[86:89], v[166:169], v[30:33]
	v_mfma_f32_16x16x32_bf16 v[26:29], v[94:97], v[166:169], v[26:29]
	v_mfma_f32_16x16x32_bf16 v[22:25], v[86:89], v[194:197], v[22:25]
	v_mfma_f32_16x16x32_bf16 v[18:21], v[94:97], v[194:197], v[18:21]
	v_mfma_f32_16x16x32_bf16 v[14:17], v[86:89], v[202:205], v[14:17]
	v_mfma_f32_16x16x32_bf16 v[10:13], v[94:97], v[202:205], v[10:13]
	v_mfma_f32_16x16x32_bf16 v[6:9], v[86:89], v[210:213], v[6:9]
	v_mfma_f32_16x16x32_bf16 v[2:5], v[94:97], v[210:213], v[2:5]
	v_mfma_f32_16x16x32_bf16 v[78:81], v[146:149], v[198:201], v[78:81]
	v_mfma_f32_16x16x32_bf16 v[74:77], v[154:157], v[198:201], v[74:77]
	v_mfma_f32_16x16x32_bf16 v[70:73], v[146:149], v[206:209], v[70:73]
	v_mfma_f32_16x16x32_bf16 v[66:69], v[154:157], v[206:209], v[66:69]
	v_mfma_f32_16x16x32_bf16 v[82:85], v[146:149], v[162:165], v[110:113]
	v_mfma_f32_16x16x32_bf16 v[86:89], v[154:157], v[162:165], v[106:109]
	v_mfma_f32_16x16x32_bf16 v[90:93], v[146:149], v[184:187], v[102:105]
	v_mfma_f32_16x16x32_bf16 v[94:97], v[154:157], v[184:187], v[98:101]
	v_mfma_f32_16x16x32_bf16 v[78:81], v[150:153], v[202:205], v[78:81]
	v_mfma_f32_16x16x32_bf16 v[74:77], v[158:161], v[202:205], v[74:77]
	v_mfma_f32_16x16x32_bf16 v[70:73], v[150:153], v[210:213], v[70:73]
	v_mfma_f32_16x16x32_bf16 v[66:69], v[158:161], v[210:213], v[66:69]
	v_mfma_f32_16x16x32_bf16 v[82:85], v[150:153], v[166:169], v[82:85]
	v_mfma_f32_16x16x32_bf16 v[86:89], v[158:161], v[166:169], v[86:89]
	v_mfma_f32_16x16x32_bf16 v[90:93], v[150:153], v[194:197], v[90:93]
	v_mfma_f32_16x16x32_bf16 v[94:97], v[158:161], v[194:197], v[94:97]
	s_barrier
	s_add_i32 s54, 0, 0x18000
	s_add_i32 s61, 0, 0x1c000
	v_add_u32_e32 v110, s54, v242
	v_add_u32_e32 v158, s61, v242
	ds_read_b128 v[98:101], v110
	ds_read_b128 v[102:105], v110 offset:1024
	ds_read_b128 v[106:109], v110 offset:2048
	ds_read_b128 v[110:113], v110 offset:3072
	ds_read_b128 v[146:149], v158
	ds_read_b128 v[150:153], v158 offset:1024
	ds_read_b128 v[154:157], v158 offset:2048
	ds_read_b128 v[158:161], v158 offset:3072
	s_add_u32 s12, s12, 0x40000
	s_addc_u32 s13, s13, 0
	s_mov_b32 m0, s64
	v_lshl_add_u64 v[222:223], s[12:13], 0, v[176:177]
	ds_read_b128 v[162:165], v243 offset:32768
	ds_read_b128 v[166:169], v243 offset:33792
	ds_read_b128 v[184:187], v243 offset:34816
	ds_read_b128 v[194:197], v243 offset:35840
	ds_read_b128 v[198:201], v243 offset:36864
	ds_read_b128 v[202:205], v243 offset:37888
	ds_read_b128 v[206:209], v243 offset:38912
	ds_read_b128 v[210:213], v243 offset:39936
	global_load_lds_dwordx4 v[222:223], off
	v_lshl_add_u64 v[222:223], s[12:13], 0, v[172:173]
	s_mov_b32 m0, s65
	s_nop 0
	global_load_lds_dwordx4 v[222:223], off
	s_waitcnt vmcnt(8)
	s_waitcnt lgkmcnt(0)
	s_barrier
	s_waitcnt lgkmcnt(0)
	v_mfma_f32_16x16x32_bf16 v[62:65], v[98:101], v[162:165], v[62:65]
	v_mfma_f32_16x16x32_bf16 v[58:61], v[106:109], v[162:165], v[58:61]
	v_mfma_f32_16x16x32_bf16 v[54:57], v[98:101], v[184:187], v[54:57]
	v_mfma_f32_16x16x32_bf16 v[50:53], v[106:109], v[184:187], v[50:53]
	v_mfma_f32_16x16x32_bf16 v[46:49], v[98:101], v[198:201], v[46:49]
	v_mfma_f32_16x16x32_bf16 v[42:45], v[106:109], v[198:201], v[42:45]
	v_mfma_f32_16x16x32_bf16 v[38:41], v[98:101], v[206:209], v[38:41]
	v_mfma_f32_16x16x32_bf16 v[34:37], v[106:109], v[206:209], v[34:37]
	v_mfma_f32_16x16x32_bf16 v[62:65], v[102:105], v[166:169], v[62:65]
	v_mfma_f32_16x16x32_bf16 v[58:61], v[110:113], v[166:169], v[58:61]
	v_mfma_f32_16x16x32_bf16 v[54:57], v[102:105], v[194:197], v[54:57]
	v_mfma_f32_16x16x32_bf16 v[50:53], v[110:113], v[194:197], v[50:53]
	v_mfma_f32_16x16x32_bf16 v[46:49], v[102:105], v[202:205], v[46:49]
	v_mfma_f32_16x16x32_bf16 v[42:45], v[110:113], v[202:205], v[42:45]
	v_mfma_f32_16x16x32_bf16 v[38:41], v[102:105], v[210:213], v[38:41]
	v_mfma_f32_16x16x32_bf16 v[34:37], v[110:113], v[210:213], v[34:37]
	v_mfma_f32_16x16x32_bf16 v[142:145], v[146:149], v[162:165], v[142:145]
	v_mfma_f32_16x16x32_bf16 v[138:141], v[154:157], v[162:165], v[138:141]
	v_mfma_f32_16x16x32_bf16 v[134:137], v[146:149], v[184:187], v[134:137]
	v_mfma_f32_16x16x32_bf16 v[130:133], v[154:157], v[184:187], v[130:133]
	v_mfma_f32_16x16x32_bf16 v[126:129], v[146:149], v[198:201], v[126:129]
	v_mfma_f32_16x16x32_bf16 v[122:125], v[154:157], v[198:201], v[122:125]
	v_mfma_f32_16x16x32_bf16 v[118:121], v[146:149], v[206:209], v[118:121]
	v_mfma_f32_16x16x32_bf16 v[114:117], v[154:157], v[206:209], v[114:117]
	v_mfma_f32_16x16x32_bf16 v[142:145], v[150:153], v[166:169], v[142:145]
	v_mfma_f32_16x16x32_bf16 v[138:141], v[158:161], v[166:169], v[138:141]
	v_mfma_f32_16x16x32_bf16 v[134:137], v[150:153], v[194:197], v[134:137]
	v_mfma_f32_16x16x32_bf16 v[130:133], v[158:161], v[194:197], v[130:133]
	v_mfma_f32_16x16x32_bf16 v[126:129], v[150:153], v[202:205], v[126:129]
	v_mfma_f32_16x16x32_bf16 v[122:125], v[158:161], v[202:205], v[122:125]
	v_mfma_f32_16x16x32_bf16 v[118:121], v[150:153], v[210:213], v[118:121]
	v_mfma_f32_16x16x32_bf16 v[114:117], v[158:161], v[210:213], v[114:117]
	s_barrier
	s_add_i32 s12, s54, s28
	v_lshl_add_u64 v[214:215], v[214:215], 0, s[72:73]
	s_mov_b32 m0, s12
	ds_read_b128 v[162:165], v243 offset:49152
	ds_read_b128 v[166:169], v243 offset:50176
	ds_read_b128 v[184:187], v243 offset:51200
	ds_read_b128 v[194:197], v243 offset:52224
	ds_read_b128 v[198:201], v243 offset:53248
	ds_read_b128 v[202:205], v243 offset:54272
	ds_read_b128 v[206:209], v243 offset:55296
	ds_read_b128 v[210:213], v243 offset:56320
	global_load_lds_dwordx4 v[214:215], off
	s_add_i32 m0, s12, 0x2000
	s_add_u32 s10, s10, 0x40080
	v_lshl_add_u64 v[214:215], v[216:217], 0, s[72:73]
	s_addc_u32 s11, s11, 0
	s_add_i32 s12, s61, s28
	global_load_lds_dwordx4 v[214:215], off
	v_lshl_add_u64 v[214:215], s[10:11], 0, v[174:175]
	s_mov_b32 m0, s12
	s_nop 0
	global_load_lds_dwordx4 v[214:215], off
	v_lshl_add_u64 v[214:215], s[10:11], 0, v[170:171]
	s_add_i32 m0, s12, 0x2000
	s_nop 0
	global_load_lds_dwordx4 v[214:215], off
	v_lshl_add_u64 v[214:215], v[218:219], 0, s[72:73]
	s_mov_b32 m0, s66
	s_nop 0
	global_load_lds_dwordx4 v[214:215], off
	v_lshl_add_u64 v[214:215], v[220:221], 0, s[72:73]
	s_mov_b32 m0, s67
	s_nop 0
	global_load_lds_dwordx4 v[214:215], off
	s_waitcnt vmcnt(8)
	s_waitcnt lgkmcnt(0)
	s_barrier
	s_waitcnt lgkmcnt(0)
	v_mfma_f32_16x16x32_bf16 v[30:33], v[98:101], v[162:165], v[30:33]
	v_mfma_f32_16x16x32_bf16 v[26:29], v[106:109], v[162:165], v[26:29]
	v_mfma_f32_16x16x32_bf16 v[22:25], v[98:101], v[184:187], v[22:25]
	v_mfma_f32_16x16x32_bf16 v[18:21], v[106:109], v[184:187], v[18:21]
	v_mfma_f32_16x16x32_bf16 v[14:17], v[98:101], v[198:201], v[14:17]
	v_mfma_f32_16x16x32_bf16 v[10:13], v[106:109], v[198:201], v[10:13]
	v_mfma_f32_16x16x32_bf16 v[6:9], v[98:101], v[206:209], v[6:9]
	v_mfma_f32_16x16x32_bf16 v[2:5], v[106:109], v[206:209], v[2:5]
	v_mfma_f32_16x16x32_bf16 v[30:33], v[102:105], v[166:169], v[30:33]
	v_mfma_f32_16x16x32_bf16 v[26:29], v[110:113], v[166:169], v[26:29]
	v_mfma_f32_16x16x32_bf16 v[22:25], v[102:105], v[194:197], v[22:25]
	v_mfma_f32_16x16x32_bf16 v[18:21], v[110:113], v[194:197], v[18:21]
	v_mfma_f32_16x16x32_bf16 v[14:17], v[102:105], v[202:205], v[14:17]
	v_mfma_f32_16x16x32_bf16 v[10:13], v[110:113], v[202:205], v[10:13]
	v_mfma_f32_16x16x32_bf16 v[6:9], v[102:105], v[210:213], v[6:9]
	v_mfma_f32_16x16x32_bf16 v[2:5], v[110:113], v[210:213], v[2:5]
	v_mfma_f32_16x16x32_bf16 v[82:85], v[146:149], v[162:165], v[82:85]
	v_mfma_f32_16x16x32_bf16 v[110:113], v[150:153], v[166:169], v[82:85]
	v_mfma_f32_16x16x32_bf16 v[82:85], v[154:157], v[162:165], v[86:89]
	v_mfma_f32_16x16x32_bf16 v[106:109], v[158:161], v[166:169], v[82:85]
	v_mfma_f32_16x16x32_bf16 v[82:85], v[146:149], v[184:187], v[90:93]
	v_mfma_f32_16x16x32_bf16 v[102:105], v[150:153], v[194:197], v[82:85]
	v_mfma_f32_16x16x32_bf16 v[82:85], v[154:157], v[184:187], v[94:97]
	v_mfma_f32_16x16x32_bf16 v[78:81], v[146:149], v[198:201], v[78:81]
	v_mfma_f32_16x16x32_bf16 v[74:77], v[154:157], v[198:201], v[74:77]
	v_mfma_f32_16x16x32_bf16 v[70:73], v[146:149], v[206:209], v[70:73]
	v_mfma_f32_16x16x32_bf16 v[66:69], v[154:157], v[206:209], v[66:69]
	v_mfma_f32_16x16x32_bf16 v[98:101], v[158:161], v[194:197], v[82:85]
	v_mfma_f32_16x16x32_bf16 v[78:81], v[150:153], v[202:205], v[78:81]
	v_mfma_f32_16x16x32_bf16 v[74:77], v[158:161], v[202:205], v[74:77]
	v_mfma_f32_16x16x32_bf16 v[70:73], v[150:153], v[210:213], v[70:73]
	v_mfma_f32_16x16x32_bf16 v[66:69], v[158:161], v[210:213], v[66:69]
	s_barrier
	s_add_i32 s23, s23, 2
	s_add_u32 s8, s8, 0x100
	s_addc_u32 s9, s9, 0
	s_add_u32 s21, s21, 0x100
	s_addc_u32 s22, s22, 0
	s_cmp_gt_u32 s23, 13
	s_cbranch_scc0 .LBB0_520
	s_and_b64 vcc, exec, s[40:41]
	s_cbranch_vccz .LBB0_523
	s_barrier

.LBB0_1245:
	s_add_u32 s28, s22, 0xfff80080
	s_addc_u32 s29, s23, -1
	s_add_i32 s71, 0, 0x10000
	s_cmp_eq_u32 s70, 28
	s_cselect_b32 s35, s17, s29
	s_cselect_b32 s34, s66, s28
	s_cselect_b32 s29, s15, s69
	s_cselect_b32 s28, s67, s68
	s_add_i32 s76, 0, 0x14000
	v_add_u32_e32 v106, s71, v220
	v_add_u32_e32 v158, s76, v220
	ds_read_b128 v[90:93], v106
	ds_read_b128 v[94:97], v106 offset:1024
	ds_read_b128 v[98:101], v106 offset:2048
	ds_read_b128 v[106:109], v106 offset:3072
	ds_read_b128 v[146:149], v158
	ds_read_b128 v[150:153], v158 offset:1024
	ds_read_b128 v[154:157], v158 offset:2048
	ds_read_b128 v[158:161], v158 offset:3072
	v_lshl_add_u64 v[214:215], s[22:23], 0, v[190:191]
	s_add_i32 m0, s48, 0xc000
	ds_read_b128 v[162:165], v221
	ds_read_b128 v[166:169], v221 offset:1024
	ds_read_b128 v[184:187], v221 offset:2048
	ds_read_b128 v[194:197], v221 offset:3072
	ds_read_b128 v[198:201], v221 offset:4096
	ds_read_b128 v[202:205], v221 offset:5120
	ds_read_b128 v[206:209], v221 offset:6144
	ds_read_b128 v[210:213], v221 offset:7168
	global_load_lds_dwordx4 v[214:215], off
	v_lshl_add_u64 v[214:215], s[22:23], 0, v[192:193]
	s_add_i32 m0, s48, 0xe000
	s_nop 0
	global_load_lds_dwordx4 v[214:215], off
	s_waitcnt vmcnt(8)
	s_waitcnt lgkmcnt(0)
	s_barrier
	s_waitcnt lgkmcnt(0)
	v_mfma_f32_16x16x32_bf16 v[142:145], v[90:93], v[162:165], v[142:145]
	v_mfma_f32_16x16x32_bf16 v[138:141], v[98:101], v[162:165], v[138:141]
	v_mfma_f32_16x16x32_bf16 v[126:129], v[90:93], v[184:187], v[126:129]
	v_mfma_f32_16x16x32_bf16 v[122:125], v[98:101], v[184:187], v[122:125]
	v_mfma_f32_16x16x32_bf16 v[110:113], v[90:93], v[198:201], v[110:113]
	v_mfma_f32_16x16x32_bf16 v[102:105], v[98:101], v[198:201], v[102:105]
	v_mfma_f32_16x16x32_bf16 v[78:81], v[90:93], v[206:209], v[78:81]
	v_mfma_f32_16x16x32_bf16 v[74:77], v[98:101], v[206:209], v[74:77]
	v_mfma_f32_16x16x32_bf16 v[142:145], v[94:97], v[166:169], v[142:145]
	v_mfma_f32_16x16x32_bf16 v[138:141], v[106:109], v[166:169], v[138:141]
	v_mfma_f32_16x16x32_bf16 v[126:129], v[94:97], v[194:197], v[126:129]
	v_mfma_f32_16x16x32_bf16 v[122:125], v[106:109], v[194:197], v[122:125]
	v_mfma_f32_16x16x32_bf16 v[110:113], v[94:97], v[202:205], v[110:113]
	v_mfma_f32_16x16x32_bf16 v[102:105], v[106:109], v[202:205], v[102:105]
	v_mfma_f32_16x16x32_bf16 v[78:81], v[94:97], v[210:213], v[78:81]
	v_mfma_f32_16x16x32_bf16 v[74:77], v[106:109], v[210:213], v[74:77]
	v_mfma_f32_16x16x32_bf16 v[134:137], v[146:149], v[162:165], v[134:137]
	v_mfma_f32_16x16x32_bf16 v[130:133], v[154:157], v[162:165], v[130:133]
	v_mfma_f32_16x16x32_bf16 v[118:121], v[146:149], v[184:187], v[118:121]
	v_mfma_f32_16x16x32_bf16 v[114:117], v[154:157], v[184:187], v[114:117]
	v_mfma_f32_16x16x32_bf16 v[86:89], v[146:149], v[198:201], v[86:89]
	v_mfma_f32_16x16x32_bf16 v[82:85], v[154:157], v[198:201], v[82:85]
	v_mfma_f32_16x16x32_bf16 v[70:73], v[146:149], v[206:209], v[70:73]
	v_mfma_f32_16x16x32_bf16 v[66:69], v[154:157], v[206:209], v[66:69]
	v_mfma_f32_16x16x32_bf16 v[134:137], v[150:153], v[166:169], v[134:137]
	v_mfma_f32_16x16x32_bf16 v[130:133], v[158:161], v[166:169], v[130:133]
	v_mfma_f32_16x16x32_bf16 v[118:121], v[150:153], v[194:197], v[118:121]
	v_mfma_f32_16x16x32_bf16 v[114:117], v[158:161], v[194:197], v[114:117]
	v_mfma_f32_16x16x32_bf16 v[86:89], v[150:153], v[202:205], v[86:89]
	v_mfma_f32_16x16x32_bf16 v[82:85], v[158:161], v[202:205], v[82:85]
	v_mfma_f32_16x16x32_bf16 v[70:73], v[150:153], v[210:213], v[70:73]
	v_mfma_f32_16x16x32_bf16 v[66:69], v[158:161], v[210:213], v[66:69]
	s_barrier
	s_add_i32 s71, s71, s43
	v_lshl_add_u64 v[214:215], s[28:29], 0, v[174:175]
	s_mov_b32 m0, s71
	ds_read_b128 v[162:165], v221 offset:16384
	ds_read_b128 v[166:169], v221 offset:17408
	ds_read_b128 v[184:187], v221 offset:18432
	ds_read_b128 v[194:197], v221 offset:19456
	ds_read_b128 v[198:201], v221 offset:20480
	ds_read_b128 v[202:205], v221 offset:21504
	ds_read_b128 v[206:209], v221 offset:22528
	ds_read_b128 v[210:213], v221 offset:23552
	global_load_lds_dwordx4 v[214:215], off
	s_add_i32 m0, s71, 0x2000
	s_add_u32 s74, s28, 0x80000
	v_lshl_add_u64 v[216:217], s[28:29], 0, v[170:171]
	s_addc_u32 s75, s29, 0
	s_add_i32 s71, s76, s43
	global_load_lds_dwordx4 v[216:217], off
	v_lshl_add_u64 v[218:219], s[74:75], 0, v[174:175]
	s_mov_b32 m0, s71
	v_lshl_add_u64 v[222:223], s[34:35], 0, v[172:173]
	global_load_lds_dwordx4 v[218:219], off
	v_lshl_add_u64 v[218:219], s[74:75], 0, v[170:171]
	s_add_i32 m0, s71, 0x2000
	s_nop 0
	global_load_lds_dwordx4 v[218:219], off
	v_lshl_add_u64 v[218:219], s[34:35], 0, v[176:177]
	s_mov_b32 m0, s48
	s_nop 0
	global_load_lds_dwordx4 v[218:219], off
	s_mov_b32 m0, s49
	s_nop 0
	global_load_lds_dwordx4 v[222:223], off
	s_waitcnt vmcnt(8)
	s_waitcnt lgkmcnt(0)
	s_barrier
	s_waitcnt lgkmcnt(0)
	v_mfma_f32_16x16x32_bf16 v[62:65], v[90:93], v[162:165], v[62:65]
	v_mfma_f32_16x16x32_bf16 v[58:61], v[98:101], v[162:165], v[58:61]
	v_mfma_f32_16x16x32_bf16 v[46:49], v[90:93], v[184:187], v[46:49]
	v_mfma_f32_16x16x32_bf16 v[42:45], v[98:101], v[184:187], v[42:45]
	v_mfma_f32_16x16x32_bf16 v[30:33], v[90:93], v[198:201], v[30:33]
	v_mfma_f32_16x16x32_bf16 v[26:29], v[98:101], v[198:201], v[26:29]
	v_mfma_f32_16x16x32_bf16 v[14:17], v[90:93], v[206:209], v[14:17]
	v_mfma_f32_16x16x32_bf16 v[10:13], v[98:101], v[206:209], v[10:13]
	v_mfma_f32_16x16x32_bf16 v[62:65], v[94:97], v[166:169], v[62:65]
	v_mfma_f32_16x16x32_bf16 v[58:61], v[106:109], v[166:169], v[58:61]
	v_mfma_f32_16x16x32_bf16 v[46:49], v[94:97], v[194:197], v[46:49]
	v_mfma_f32_16x16x32_bf16 v[42:45], v[106:109], v[194:197], v[42:45]
	v_mfma_f32_16x16x32_bf16 v[30:33], v[94:97], v[202:205], v[30:33]
	v_mfma_f32_16x16x32_bf16 v[26:29], v[106:109], v[202:205], v[26:29]
	v_mfma_f32_16x16x32_bf16 v[14:17], v[94:97], v[210:213], v[14:17]
	v_mfma_f32_16x16x32_bf16 v[10:13], v[106:109], v[210:213], v[10:13]
	v_mfma_f32_16x16x32_bf16 v[54:57], v[146:149], v[162:165], v[54:57]
	v_mfma_f32_16x16x32_bf16 v[50:53], v[154:157], v[162:165], v[50:53]
	v_mfma_f32_16x16x32_bf16 v[38:41], v[146:149], v[184:187], v[38:41]
	v_mfma_f32_16x16x32_bf16 v[34:37], v[154:157], v[184:187], v[34:37]
	v_mfma_f32_16x16x32_bf16 v[22:25], v[146:149], v[198:201], v[22:25]
	v_mfma_f32_16x16x32_bf16 v[18:21], v[154:157], v[198:201], v[18:21]
	v_mfma_f32_16x16x32_bf16 v[6:9], v[146:149], v[206:209], v[6:9]
	v_mfma_f32_16x16x32_bf16 v[2:5], v[154:157], v[206:209], v[2:5]
	v_mfma_f32_16x16x32_bf16 v[54:57], v[150:153], v[166:169], v[54:57]
	v_mfma_f32_16x16x32_bf16 v[50:53], v[158:161], v[166:169], v[50:53]
	v_mfma_f32_16x16x32_bf16 v[38:41], v[150:153], v[194:197], v[38:41]
	v_mfma_f32_16x16x32_bf16 v[34:37], v[158:161], v[194:197], v[34:37]
	v_mfma_f32_16x16x32_bf16 v[22:25], v[150:153], v[202:205], v[22:25]
	v_mfma_f32_16x16x32_bf16 v[18:21], v[158:161], v[202:205], v[18:21]
	v_mfma_f32_16x16x32_bf16 v[6:9], v[150:153], v[210:213], v[6:9]
	v_mfma_f32_16x16x32_bf16 v[2:5], v[158:161], v[210:213], v[2:5]
	s_barrier
	s_add_i32 s71, 0, 0x18000
	s_add_i32 s74, 0, 0x1c000
	v_add_u32_e32 v106, s71, v220
	v_add_u32_e32 v158, s74, v220
	ds_read_b128 v[90:93], v106
	ds_read_b128 v[94:97], v106 offset:1024
	ds_read_b128 v[98:101], v106 offset:2048
	ds_read_b128 v[106:109], v106 offset:3072
	ds_read_b128 v[146:149], v158
	ds_read_b128 v[150:153], v158 offset:1024
	ds_read_b128 v[154:157], v158 offset:2048
	ds_read_b128 v[158:161], v158 offset:3072
	s_add_u32 s34, s34, 0x80000
	s_addc_u32 s35, s35, 0
	s_mov_b32 m0, s50
	v_lshl_add_u64 v[224:225], s[34:35], 0, v[176:177]
	ds_read_b128 v[162:165], v221 offset:32768
	ds_read_b128 v[166:169], v221 offset:33792
	ds_read_b128 v[184:187], v221 offset:34816
	ds_read_b128 v[194:197], v221 offset:35840
	ds_read_b128 v[198:201], v221 offset:36864
	ds_read_b128 v[202:205], v221 offset:37888
	ds_read_b128 v[206:209], v221 offset:38912
	ds_read_b128 v[210:213], v221 offset:39936
	global_load_lds_dwordx4 v[224:225], off
	v_lshl_add_u64 v[224:225], s[34:35], 0, v[172:173]
	s_mov_b32 m0, s51
	s_nop 0
	global_load_lds_dwordx4 v[224:225], off
	s_waitcnt vmcnt(8)
	s_waitcnt lgkmcnt(0)
	s_barrier
	s_waitcnt lgkmcnt(0)
	v_mfma_f32_16x16x32_bf16 v[142:145], v[90:93], v[162:165], v[142:145]
	v_mfma_f32_16x16x32_bf16 v[138:141], v[98:101], v[162:165], v[138:141]
	v_mfma_f32_16x16x32_bf16 v[126:129], v[90:93], v[184:187], v[126:129]
	v_mfma_f32_16x16x32_bf16 v[122:125], v[98:101], v[184:187], v[122:125]
	v_mfma_f32_16x16x32_bf16 v[110:113], v[90:93], v[198:201], v[110:113]
	v_mfma_f32_16x16x32_bf16 v[102:105], v[98:101], v[198:201], v[102:105]
	v_mfma_f32_16x16x32_bf16 v[78:81], v[90:93], v[206:209], v[78:81]
	v_mfma_f32_16x16x32_bf16 v[74:77], v[98:101], v[206:209], v[74:77]
	v_mfma_f32_16x16x32_bf16 v[142:145], v[94:97], v[166:169], v[142:145]
	v_mfma_f32_16x16x32_bf16 v[138:141], v[106:109], v[166:169], v[138:141]
	v_mfma_f32_16x16x32_bf16 v[126:129], v[94:97], v[194:197], v[126:129]
	v_mfma_f32_16x16x32_bf16 v[122:125], v[106:109], v[194:197], v[122:125]
	v_mfma_f32_16x16x32_bf16 v[110:113], v[94:97], v[202:205], v[110:113]
	v_mfma_f32_16x16x32_bf16 v[102:105], v[106:109], v[202:205], v[102:105]
	v_mfma_f32_16x16x32_bf16 v[78:81], v[94:97], v[210:213], v[78:81]
	v_mfma_f32_16x16x32_bf16 v[74:77], v[106:109], v[210:213], v[74:77]
	v_mfma_f32_16x16x32_bf16 v[134:137], v[146:149], v[162:165], v[134:137]
	v_mfma_f32_16x16x32_bf16 v[130:133], v[154:157], v[162:165], v[130:133]
	v_mfma_f32_16x16x32_bf16 v[118:121], v[146:149], v[184:187], v[118:121]
	v_mfma_f32_16x16x32_bf16 v[114:117], v[154:157], v[184:187], v[114:117]
	v_mfma_f32_16x16x32_bf16 v[86:89], v[146:149], v[198:201], v[86:89]
	v_mfma_f32_16x16x32_bf16 v[82:85], v[154:157], v[198:201], v[82:85]
	v_mfma_f32_16x16x32_bf16 v[70:73], v[146:149], v[206:209], v[70:73]
	v_mfma_f32_16x16x32_bf16 v[66:69], v[154:157], v[206:209], v[66:69]
	v_mfma_f32_16x16x32_bf16 v[134:137], v[150:153], v[166:169], v[134:137]
	v_mfma_f32_16x16x32_bf16 v[130:133], v[158:161], v[166:169], v[130:133]
	v_mfma_f32_16x16x32_bf16 v[118:121], v[150:153], v[194:197], v[118:121]
	v_mfma_f32_16x16x32_bf16 v[114:117], v[158:161], v[194:197], v[114:117]
	v_mfma_f32_16x16x32_bf16 v[86:89], v[150:153], v[202:205], v[86:89]
	v_mfma_f32_16x16x32_bf16 v[82:85], v[158:161], v[202:205], v[82:85]
	v_mfma_f32_16x16x32_bf16 v[70:73], v[150:153], v[210:213], v[70:73]
	v_mfma_f32_16x16x32_bf16 v[66:69], v[158:161], v[210:213], v[66:69]
	s_barrier
	s_add_i32 s34, s71, s43
	v_lshl_add_u64 v[214:215], v[214:215], 0, s[72:73]
	s_mov_b32 m0, s34
	ds_read_b128 v[162:165], v221 offset:49152
	ds_read_b128 v[166:169], v221 offset:50176
	ds_read_b128 v[184:187], v221 offset:51200
	ds_read_b128 v[194:197], v221 offset:52224
	ds_read_b128 v[198:201], v221 offset:53248
	ds_read_b128 v[202:205], v221 offset:54272
	ds_read_b128 v[206:209], v221 offset:55296
	ds_read_b128 v[210:213], v221 offset:56320
	global_load_lds_dwordx4 v[214:215], off
	s_add_i32 m0, s34, 0x2000
	s_add_u32 s28, s28, 0x80080
	v_lshl_add_u64 v[214:215], v[216:217], 0, s[72:73]
	s_addc_u32 s29, s29, 0
	s_add_i32 s34, s74, s43
	global_load_lds_dwordx4 v[214:215], off
	v_lshl_add_u64 v[214:215], s[28:29], 0, v[174:175]
	s_mov_b32 m0, s34
	s_nop 0
	global_load_lds_dwordx4 v[214:215], off
	v_lshl_add_u64 v[214:215], s[28:29], 0, v[170:171]
	s_add_i32 m0, s34, 0x2000
	s_nop 0
	global_load_lds_dwordx4 v[214:215], off
	v_lshl_add_u64 v[214:215], v[218:219], 0, s[72:73]
	s_mov_b32 m0, s60
	s_nop 0
	global_load_lds_dwordx4 v[214:215], off
	v_lshl_add_u64 v[214:215], v[222:223], 0, s[72:73]
	s_mov_b32 m0, s61
	s_nop 0
	global_load_lds_dwordx4 v[214:215], off
	s_waitcnt vmcnt(8)
	s_waitcnt lgkmcnt(0)
	s_barrier
	s_waitcnt lgkmcnt(0)
	v_mfma_f32_16x16x32_bf16 v[62:65], v[90:93], v[162:165], v[62:65]
	v_mfma_f32_16x16x32_bf16 v[58:61], v[98:101], v[162:165], v[58:61]
	v_mfma_f32_16x16x32_bf16 v[46:49], v[90:93], v[184:187], v[46:49]
	v_mfma_f32_16x16x32_bf16 v[42:45], v[98:101], v[184:187], v[42:45]
	v_mfma_f32_16x16x32_bf16 v[30:33], v[90:93], v[198:201], v[30:33]
	v_mfma_f32_16x16x32_bf16 v[26:29], v[98:101], v[198:201], v[26:29]
	v_mfma_f32_16x16x32_bf16 v[14:17], v[90:93], v[206:209], v[14:17]
	v_mfma_f32_16x16x32_bf16 v[10:13], v[98:101], v[206:209], v[10:13]
	v_mfma_f32_16x16x32_bf16 v[62:65], v[94:97], v[166:169], v[62:65]
	v_mfma_f32_16x16x32_bf16 v[58:61], v[106:109], v[166:169], v[58:61]
	v_mfma_f32_16x16x32_bf16 v[46:49], v[94:97], v[194:197], v[46:49]
	v_mfma_f32_16x16x32_bf16 v[42:45], v[106:109], v[194:197], v[42:45]
	v_mfma_f32_16x16x32_bf16 v[30:33], v[94:97], v[202:205], v[30:33]
	v_mfma_f32_16x16x32_bf16 v[26:29], v[106:109], v[202:205], v[26:29]
	v_mfma_f32_16x16x32_bf16 v[14:17], v[94:97], v[210:213], v[14:17]
	v_mfma_f32_16x16x32_bf16 v[10:13], v[106:109], v[210:213], v[10:13]
	v_mfma_f32_16x16x32_bf16 v[54:57], v[146:149], v[162:165], v[54:57]
	v_mfma_f32_16x16x32_bf16 v[50:53], v[154:157], v[162:165], v[50:53]
	v_mfma_f32_16x16x32_bf16 v[38:41], v[146:149], v[184:187], v[38:41]
	v_mfma_f32_16x16x32_bf16 v[34:37], v[154:157], v[184:187], v[34:37]
	v_mfma_f32_16x16x32_bf16 v[22:25], v[146:149], v[198:201], v[22:25]
	v_mfma_f32_16x16x32_bf16 v[18:21], v[154:157], v[198:201], v[18:21]
	v_mfma_f32_16x16x32_bf16 v[6:9], v[146:149], v[206:209], v[6:9]
	v_mfma_f32_16x16x32_bf16 v[2:5], v[154:157], v[206:209], v[2:5]
	v_mfma_f32_16x16x32_bf16 v[54:57], v[150:153], v[166:169], v[54:57]
	v_mfma_f32_16x16x32_bf16 v[50:53], v[158:161], v[166:169], v[50:53]
	v_mfma_f32_16x16x32_bf16 v[38:41], v[150:153], v[194:197], v[38:41]
	v_mfma_f32_16x16x32_bf16 v[34:37], v[158:161], v[194:197], v[34:37]
	v_mfma_f32_16x16x32_bf16 v[22:25], v[150:153], v[202:205], v[22:25]
	v_mfma_f32_16x16x32_bf16 v[18:21], v[158:161], v[202:205], v[18:21]
	v_mfma_f32_16x16x32_bf16 v[6:9], v[150:153], v[210:213], v[6:9]
	v_mfma_f32_16x16x32_bf16 v[2:5], v[158:161], v[210:213], v[2:5]
	s_barrier
	s_add_i32 s70, s70, 2
	s_add_u32 s22, s22, 0x100
	s_addc_u32 s23, s23, 0
	s_add_u32 s68, s68, 0x100
	s_addc_u32 s69, s69, 0
	s_cmp_gt_u32 s70, 29
	s_cbranch_scc0 .LBB0_1245
	v_mov_b32_e32 v146, v1
	v_mov_b32_e32 v90, v189
	s_cmp_lt_i32 s65, 32
	s_mov_b64 s[22:23], 0
	s_cbranch_scc1 .LBB0_1248
	s_sub_i32 s15, s65, 32
	s_lshr_b32 s15, s15, 2
	s_add_i32 s15, s15, 1
	s_mul_hi_u32 s23, s15, 0x1800
	s_mul_i32 s22, s15, 0x1800

.LBB0_1330:
	s_add_u32 s8, s6, 0xfffc0080
	s_addc_u32 s9, s7, -1
	s_add_i32 s57, 0, 0x10000
	s_cmp_eq_u32 s19, 12
	s_cselect_b32 s11, s12, s9
	s_cselect_b32 s10, s13, s8
	s_cselect_b32 s9, s14, s18
	s_cselect_b32 s8, s15, s17
	s_add_i32 s65, 0, 0x14000
	v_add_u32_e32 v90, s57, v1
	v_add_u32_e32 v170, s65, v1
	ds_read_b128 v[34:37], v90
	ds_read_b128 v[38:41], v90 offset:1024
	ds_read_b128 v[86:89], v90 offset:2048
	ds_read_b128 v[90:93], v90 offset:3072
	ds_read_b128 v[146:149], v170
	ds_read_b128 v[162:165], v170 offset:1024
	ds_read_b128 v[166:169], v170 offset:2048
	ds_read_b128 v[170:173], v170 offset:3072
	v_lshl_add_u64 v[214:215], s[6:7], 0, v[158:159]
	s_add_i32 m0, s38, 0xc000
	ds_read_b128 v[174:177], v189
	ds_read_b128 v[184:187], v189 offset:1024
	ds_read_b128 v[190:193], v189 offset:2048
	ds_read_b128 v[194:197], v189 offset:3072
	ds_read_b128 v[198:201], v189 offset:4096
	ds_read_b128 v[202:205], v189 offset:5120
	ds_read_b128 v[206:209], v189 offset:6144
	ds_read_b128 v[210:213], v189 offset:7168
	global_load_lds_dwordx4 v[214:215], off
	v_lshl_add_u64 v[214:215], s[6:7], 0, v[160:161]
	s_add_i32 m0, s38, 0xe000
	s_nop 0
	global_load_lds_dwordx4 v[214:215], off
	s_waitcnt vmcnt(8)
	s_waitcnt lgkmcnt(0)
	s_barrier
	s_waitcnt lgkmcnt(0)
	v_mfma_f32_16x16x32_bf16 v[94:97], v[34:37], v[174:177], v[94:97]
	v_mfma_f32_16x16x32_bf16 v[142:145], v[86:89], v[174:177], v[142:145]
	v_mfma_f32_16x16x32_bf16 v[78:81], v[34:37], v[190:193], v[78:81]
	v_mfma_f32_16x16x32_bf16 v[30:33], v[86:89], v[190:193], v[30:33]
	v_mfma_f32_16x16x32_bf16 v[74:77], v[34:37], v[198:201], v[74:77]
	v_mfma_f32_16x16x32_bf16 v[26:29], v[86:89], v[198:201], v[26:29]
	v_mfma_f32_16x16x32_bf16 v[118:121], v[34:37], v[206:209], v[118:121]
	v_mfma_f32_16x16x32_bf16 v[110:113], v[86:89], v[206:209], v[110:113]
	v_mfma_f32_16x16x32_bf16 v[94:97], v[38:41], v[184:187], v[94:97]
	v_mfma_f32_16x16x32_bf16 v[142:145], v[90:93], v[184:187], v[142:145]
	v_mfma_f32_16x16x32_bf16 v[78:81], v[38:41], v[194:197], v[78:81]
	v_mfma_f32_16x16x32_bf16 v[30:33], v[90:93], v[194:197], v[30:33]
	v_mfma_f32_16x16x32_bf16 v[74:77], v[38:41], v[202:205], v[74:77]
	v_mfma_f32_16x16x32_bf16 v[26:29], v[90:93], v[202:205], v[26:29]
	v_mfma_f32_16x16x32_bf16 v[118:121], v[38:41], v[210:213], v[118:121]
	v_mfma_f32_16x16x32_bf16 v[110:113], v[90:93], v[210:213], v[110:113]
	v_mfma_f32_16x16x32_bf16 v[82:85], v[146:149], v[174:177], v[82:85]
	v_mfma_f32_16x16x32_bf16 v[138:141], v[166:169], v[174:177], v[138:141]
	v_mfma_f32_16x16x32_bf16 v[70:73], v[146:149], v[190:193], v[70:73]
	v_mfma_f32_16x16x32_bf16 v[22:25], v[166:169], v[190:193], v[22:25]
	v_mfma_f32_16x16x32_bf16 v[66:69], v[146:149], v[198:201], v[66:69]
	v_mfma_f32_16x16x32_bf16 v[18:21], v[166:169], v[198:201], v[18:21]
	v_mfma_f32_16x16x32_bf16 v[102:105], v[146:149], v[206:209], v[102:105]
	v_mfma_f32_16x16x32_bf16 v[98:101], v[166:169], v[206:209], v[98:101]
	v_mfma_f32_16x16x32_bf16 v[82:85], v[162:165], v[184:187], v[82:85]
	v_mfma_f32_16x16x32_bf16 v[138:141], v[170:173], v[184:187], v[138:141]
	v_mfma_f32_16x16x32_bf16 v[70:73], v[162:165], v[194:197], v[70:73]
	v_mfma_f32_16x16x32_bf16 v[22:25], v[170:173], v[194:197], v[22:25]
	v_mfma_f32_16x16x32_bf16 v[66:69], v[162:165], v[202:205], v[66:69]
	v_mfma_f32_16x16x32_bf16 v[18:21], v[170:173], v[202:205], v[18:21]
	v_mfma_f32_16x16x32_bf16 v[102:105], v[162:165], v[210:213], v[102:105]
	v_mfma_f32_16x16x32_bf16 v[98:101], v[170:173], v[210:213], v[98:101]
	s_barrier
	s_add_i32 s57, s57, s62
	v_lshl_add_u64 v[214:215], s[8:9], 0, v[154:155]
	s_mov_b32 m0, s57
	ds_read_b128 v[174:177], v189 offset:16384
	ds_read_b128 v[184:187], v189 offset:17408
	ds_read_b128 v[190:193], v189 offset:18432
	ds_read_b128 v[194:197], v189 offset:19456
	ds_read_b128 v[198:201], v189 offset:20480
	ds_read_b128 v[202:205], v189 offset:21504
	ds_read_b128 v[206:209], v189 offset:22528
	ds_read_b128 v[210:213], v189 offset:23552
	global_load_lds_dwordx4 v[214:215], off
	s_add_i32 m0, s57, 0x2000
	s_add_u32 s96, s8, 0x40000
	v_lshl_add_u64 v[216:217], s[8:9], 0, v[150:151]
	s_addc_u32 s97, s9, 0
	s_add_i32 s57, s65, s62
	global_load_lds_dwordx4 v[216:217], off
	v_lshl_add_u64 v[218:219], s[96:97], 0, v[154:155]
	s_mov_b32 m0, s57
	v_lshl_add_u64 v[220:221], s[10:11], 0, v[152:153]
	global_load_lds_dwordx4 v[218:219], off
	v_lshl_add_u64 v[218:219], s[96:97], 0, v[150:151]
	s_add_i32 m0, s57, 0x2000
	s_nop 0
	global_load_lds_dwordx4 v[218:219], off
	v_lshl_add_u64 v[218:219], s[10:11], 0, v[156:157]
	s_mov_b32 m0, s38
	s_nop 0
	global_load_lds_dwordx4 v[218:219], off
	s_mov_b32 m0, s39
	s_nop 0
	global_load_lds_dwordx4 v[220:221], off
	s_waitcnt vmcnt(8)
	s_waitcnt lgkmcnt(0)
	s_barrier
	s_waitcnt lgkmcnt(0)
	v_mfma_f32_16x16x32_bf16 v[126:129], v[34:37], v[174:177], v[126:129]
	v_mfma_f32_16x16x32_bf16 v[122:125], v[86:89], v[174:177], v[122:125]
	v_mfma_f32_16x16x32_bf16 v[54:57], v[34:37], v[190:193], v[54:57]
	v_mfma_f32_16x16x32_bf16 v[14:17], v[86:89], v[190:193], v[14:17]
	v_mfma_f32_16x16x32_bf16 v[50:53], v[34:37], v[198:201], v[50:53]
	v_mfma_f32_16x16x32_bf16 v[10:13], v[86:89], v[198:201], v[10:13]
	v_mfma_f32_16x16x32_bf16 v[34:37], v[34:37], v[206:209], v[58:61]
	v_mfma_f32_16x16x32_bf16 v[126:129], v[38:41], v[184:187], v[126:129]
	v_mfma_f32_16x16x32_bf16 v[122:125], v[90:93], v[184:187], v[122:125]
	v_mfma_f32_16x16x32_bf16 v[54:57], v[38:41], v[194:197], v[54:57]
	v_mfma_f32_16x16x32_bf16 v[14:17], v[90:93], v[194:197], v[14:17]
	v_mfma_f32_16x16x32_bf16 v[50:53], v[38:41], v[202:205], v[50:53]
	v_mfma_f32_16x16x32_bf16 v[10:13], v[90:93], v[202:205], v[10:13]
	v_mfma_f32_16x16x32_bf16 v[34:37], v[38:41], v[210:213], v[34:37]
	v_mfma_f32_16x16x32_bf16 v[38:41], v[86:89], v[206:209], v[134:137]
	v_mfma_f32_16x16x32_bf16 v[38:41], v[90:93], v[210:213], v[38:41]
	v_mfma_f32_16x16x32_bf16 v[58:61], v[146:149], v[174:177], v[114:117]
	v_mfma_f32_16x16x32_bf16 v[86:89], v[162:165], v[184:187], v[58:61]
	v_mfma_f32_16x16x32_bf16 v[58:61], v[166:169], v[174:177], v[106:109]
	v_mfma_f32_16x16x32_bf16 v[90:93], v[170:173], v[184:187], v[58:61]
	v_mfma_f32_16x16x32_bf16 v[58:61], v[146:149], v[206:209], v[62:65]
	v_mfma_f32_16x16x32_bf16 v[46:49], v[146:149], v[190:193], v[46:49]
	v_mfma_f32_16x16x32_bf16 v[6:9], v[166:169], v[190:193], v[6:9]
	v_mfma_f32_16x16x32_bf16 v[42:45], v[146:149], v[198:201], v[42:45]
	v_mfma_f32_16x16x32_bf16 v[2:5], v[166:169], v[198:201], v[2:5]
	v_mfma_f32_16x16x32_bf16 v[62:65], v[162:165], v[210:213], v[58:61]
	v_mfma_f32_16x16x32_bf16 v[58:61], v[166:169], v[206:209], v[130:133]
	v_mfma_f32_16x16x32_bf16 v[46:49], v[162:165], v[194:197], v[46:49]
	v_mfma_f32_16x16x32_bf16 v[6:9], v[170:173], v[194:197], v[6:9]
	v_mfma_f32_16x16x32_bf16 v[42:45], v[162:165], v[202:205], v[42:45]
	v_mfma_f32_16x16x32_bf16 v[2:5], v[170:173], v[202:205], v[2:5]
	v_mfma_f32_16x16x32_bf16 v[130:133], v[170:173], v[210:213], v[58:61]
	s_barrier
	s_add_i32 s57, 0, 0x18000
	s_add_i32 s65, 0, 0x1c000
	v_add_u32_e32 v134, s57, v1
	v_add_u32_e32 v170, s65, v1
	ds_read_b128 v[58:61], v134
	ds_read_b128 v[106:109], v134 offset:1024
	ds_read_b128 v[114:117], v134 offset:2048
	ds_read_b128 v[134:137], v134 offset:3072
	ds_read_b128 v[146:149], v170
	ds_read_b128 v[162:165], v170 offset:1024
	ds_read_b128 v[166:169], v170 offset:2048
	ds_read_b128 v[170:173], v170 offset:3072
	s_add_u32 s10, s10, 0x40000
	s_addc_u32 s11, s11, 0
	s_mov_b32 m0, s54
	v_lshl_add_u64 v[222:223], s[10:11], 0, v[156:157]
	ds_read_b128 v[174:177], v189 offset:32768
	ds_read_b128 v[184:187], v189 offset:33792
	ds_read_b128 v[190:193], v189 offset:34816
	ds_read_b128 v[194:197], v189 offset:35840
	ds_read_b128 v[198:201], v189 offset:36864
	ds_read_b128 v[202:205], v189 offset:37888
	ds_read_b128 v[206:209], v189 offset:38912
	ds_read_b128 v[210:213], v189 offset:39936
	global_load_lds_dwordx4 v[222:223], off
	v_lshl_add_u64 v[222:223], s[10:11], 0, v[152:153]
	s_mov_b32 m0, s40
	s_nop 0
	global_load_lds_dwordx4 v[222:223], off
	s_waitcnt vmcnt(8)
	s_waitcnt lgkmcnt(0)
	s_barrier
	s_waitcnt lgkmcnt(0)
	v_mfma_f32_16x16x32_bf16 v[94:97], v[58:61], v[174:177], v[94:97]
	v_mfma_f32_16x16x32_bf16 v[142:145], v[114:117], v[174:177], v[142:145]
	v_mfma_f32_16x16x32_bf16 v[78:81], v[58:61], v[190:193], v[78:81]
	v_mfma_f32_16x16x32_bf16 v[30:33], v[114:117], v[190:193], v[30:33]
	v_mfma_f32_16x16x32_bf16 v[74:77], v[58:61], v[198:201], v[74:77]
	v_mfma_f32_16x16x32_bf16 v[26:29], v[114:117], v[198:201], v[26:29]
	v_mfma_f32_16x16x32_bf16 v[118:121], v[58:61], v[206:209], v[118:121]
	v_mfma_f32_16x16x32_bf16 v[110:113], v[114:117], v[206:209], v[110:113]
	v_mfma_f32_16x16x32_bf16 v[94:97], v[106:109], v[184:187], v[94:97]
	v_mfma_f32_16x16x32_bf16 v[142:145], v[134:137], v[184:187], v[142:145]
	v_mfma_f32_16x16x32_bf16 v[78:81], v[106:109], v[194:197], v[78:81]
	v_mfma_f32_16x16x32_bf16 v[30:33], v[134:137], v[194:197], v[30:33]
	v_mfma_f32_16x16x32_bf16 v[74:77], v[106:109], v[202:205], v[74:77]
	v_mfma_f32_16x16x32_bf16 v[26:29], v[134:137], v[202:205], v[26:29]
	v_mfma_f32_16x16x32_bf16 v[118:121], v[106:109], v[210:213], v[118:121]
	v_mfma_f32_16x16x32_bf16 v[110:113], v[134:137], v[210:213], v[110:113]
	v_mfma_f32_16x16x32_bf16 v[82:85], v[146:149], v[174:177], v[82:85]
	v_mfma_f32_16x16x32_bf16 v[138:141], v[166:169], v[174:177], v[138:141]
	v_mfma_f32_16x16x32_bf16 v[70:73], v[146:149], v[190:193], v[70:73]
	v_mfma_f32_16x16x32_bf16 v[22:25], v[166:169], v[190:193], v[22:25]
	v_mfma_f32_16x16x32_bf16 v[66:69], v[146:149], v[198:201], v[66:69]
	v_mfma_f32_16x16x32_bf16 v[18:21], v[166:169], v[198:201], v[18:21]
	v_mfma_f32_16x16x32_bf16 v[102:105], v[146:149], v[206:209], v[102:105]
	v_mfma_f32_16x16x32_bf16 v[98:101], v[166:169], v[206:209], v[98:101]
	v_mfma_f32_16x16x32_bf16 v[82:85], v[162:165], v[184:187], v[82:85]
	v_mfma_f32_16x16x32_bf16 v[138:141], v[170:173], v[184:187], v[138:141]
	v_mfma_f32_16x16x32_bf16 v[70:73], v[162:165], v[194:197], v[70:73]
	v_mfma_f32_16x16x32_bf16 v[22:25], v[170:173], v[194:197], v[22:25]
	v_mfma_f32_16x16x32_bf16 v[66:69], v[162:165], v[202:205], v[66:69]
	v_mfma_f32_16x16x32_bf16 v[18:21], v[170:173], v[202:205], v[18:21]
	v_mfma_f32_16x16x32_bf16 v[102:105], v[162:165], v[210:213], v[102:105]
	v_mfma_f32_16x16x32_bf16 v[98:101], v[170:173], v[210:213], v[98:101]
	s_barrier
	s_add_i32 s10, s57, s62
	v_lshl_add_u64 v[214:215], v[214:215], 0, s[72:73]
	s_mov_b32 m0, s10
	ds_read_b128 v[174:177], v189 offset:49152
	ds_read_b128 v[184:187], v189 offset:50176
	ds_read_b128 v[190:193], v189 offset:51200
	ds_read_b128 v[194:197], v189 offset:52224
	ds_read_b128 v[198:201], v189 offset:53248
	ds_read_b128 v[202:205], v189 offset:54272
	ds_read_b128 v[206:209], v189 offset:55296
	ds_read_b128 v[210:213], v189 offset:56320
	global_load_lds_dwordx4 v[214:215], off
	s_add_i32 m0, s10, 0x2000
	s_add_u32 s8, s8, 0x40080
	v_lshl_add_u64 v[214:215], v[216:217], 0, s[72:73]
	s_addc_u32 s9, s9, 0
	s_add_i32 s10, s65, s62
	global_load_lds_dwordx4 v[214:215], off
	v_lshl_add_u64 v[214:215], s[8:9], 0, v[154:155]
	s_mov_b32 m0, s10
	s_nop 0
	global_load_lds_dwordx4 v[214:215], off
	v_lshl_add_u64 v[214:215], s[8:9], 0, v[150:151]
	s_add_i32 m0, s10, 0x2000
	s_nop 0
	global_load_lds_dwordx4 v[214:215], off
	v_lshl_add_u64 v[214:215], v[218:219], 0, s[72:73]
	s_mov_b32 m0, s50
	s_nop 0
	global_load_lds_dwordx4 v[214:215], off
	v_lshl_add_u64 v[214:215], v[220:221], 0, s[72:73]
	s_mov_b32 m0, s51
	s_nop 0
	global_load_lds_dwordx4 v[214:215], off
	s_waitcnt vmcnt(8)
	s_waitcnt lgkmcnt(0)
	s_barrier
	s_waitcnt lgkmcnt(0)
	v_mfma_f32_16x16x32_bf16 v[34:37], v[58:61], v[206:209], v[34:37]
	v_mfma_f32_16x16x32_bf16 v[126:129], v[58:61], v[174:177], v[126:129]
	v_mfma_f32_16x16x32_bf16 v[122:125], v[114:117], v[174:177], v[122:125]
	v_mfma_f32_16x16x32_bf16 v[54:57], v[58:61], v[190:193], v[54:57]
	v_mfma_f32_16x16x32_bf16 v[14:17], v[114:117], v[190:193], v[14:17]
	v_mfma_f32_16x16x32_bf16 v[50:53], v[58:61], v[198:201], v[50:53]
	v_mfma_f32_16x16x32_bf16 v[10:13], v[114:117], v[198:201], v[10:13]
	v_mfma_f32_16x16x32_bf16 v[58:61], v[106:109], v[210:213], v[34:37]
	v_mfma_f32_16x16x32_bf16 v[34:37], v[114:117], v[206:209], v[38:41]
	v_mfma_f32_16x16x32_bf16 v[126:129], v[106:109], v[184:187], v[126:129]
	v_mfma_f32_16x16x32_bf16 v[122:125], v[134:137], v[184:187], v[122:125]
	v_mfma_f32_16x16x32_bf16 v[54:57], v[106:109], v[194:197], v[54:57]
	v_mfma_f32_16x16x32_bf16 v[14:17], v[134:137], v[194:197], v[14:17]
	v_mfma_f32_16x16x32_bf16 v[50:53], v[106:109], v[202:205], v[50:53]
	v_mfma_f32_16x16x32_bf16 v[10:13], v[134:137], v[202:205], v[10:13]
	v_mfma_f32_16x16x32_bf16 v[134:137], v[134:137], v[210:213], v[34:37]
	v_mfma_f32_16x16x32_bf16 v[34:37], v[146:149], v[174:177], v[86:89]
	v_mfma_f32_16x16x32_bf16 v[114:117], v[162:165], v[184:187], v[34:37]
	v_mfma_f32_16x16x32_bf16 v[34:37], v[166:169], v[174:177], v[90:93]
	v_mfma_f32_16x16x32_bf16 v[106:109], v[170:173], v[184:187], v[34:37]
	v_mfma_f32_16x16x32_bf16 v[34:37], v[146:149], v[190:193], v[46:49]
	v_mfma_f32_16x16x32_bf16 v[46:49], v[162:165], v[194:197], v[34:37]
	v_mfma_f32_16x16x32_bf16 v[34:37], v[146:149], v[198:201], v[42:45]
	v_mfma_f32_16x16x32_bf16 v[42:45], v[162:165], v[202:205], v[34:37]
	v_mfma_f32_16x16x32_bf16 v[34:37], v[146:149], v[206:209], v[62:65]
	v_mfma_f32_16x16x32_bf16 v[6:9], v[166:169], v[190:193], v[6:9]
	v_mfma_f32_16x16x32_bf16 v[2:5], v[166:169], v[198:201], v[2:5]
	v_mfma_f32_16x16x32_bf16 v[62:65], v[162:165], v[210:213], v[34:37]
	v_mfma_f32_16x16x32_bf16 v[34:37], v[166:169], v[206:209], v[130:133]
	v_mfma_f32_16x16x32_bf16 v[6:9], v[170:173], v[194:197], v[6:9]
	v_mfma_f32_16x16x32_bf16 v[2:5], v[170:173], v[202:205], v[2:5]
	v_mfma_f32_16x16x32_bf16 v[130:133], v[170:173], v[210:213], v[34:37]
	s_barrier
	s_add_i32 s19, s19, 2
	s_add_u32 s6, s6, 0x100
	s_addc_u32 s7, s7, 0
	s_add_u32 s17, s17, 0x100
	s_addc_u32 s18, s18, 0
	s_cmp_gt_u32 s19, 13
	s_cbranch_scc0 .LBB0_1330
	s_and_b64 vcc, exec, s[68:69]
	s_cbranch_vccz .LBB0_1333
	s_barrier

.LBB0_1471:
	s_add_u32 s6, s28, 0x100
	s_addc_u32 s7, s29, 0
	s_add_i32 s74, 0, 0x10000
	s_cmp_eq_u32 s71, 40
	s_cselect_b32 s35, s21, s7
	s_cselect_b32 s34, s20, s6
	s_cselect_b32 s9, s23, s70
	s_cselect_b32 s8, s22, s69
	s_add_i32 s75, 0, 0x14000
	v_add_u32_e32 v86, s74, v242
	v_add_u32_e32 v158, s75, v242
	ds_read_b128 v[74:77], v86
	ds_read_b128 v[78:81], v86 offset:1024
	ds_read_b128 v[82:85], v86 offset:2048
	ds_read_b128 v[86:89], v86 offset:3072
	ds_read_b128 v[146:149], v158
	ds_read_b128 v[150:153], v158 offset:1024
	ds_read_b128 v[154:157], v158 offset:2048
	ds_read_b128 v[158:161], v158 offset:3072
	v_lshl_add_u64 v[214:215], s[28:29], 0, v[198:199]
	s_add_i32 m0, s48, 0xc000
	ds_read_b128 v[162:165], v243
	ds_read_b128 v[166:169], v243 offset:1024
	ds_read_b128 v[170:173], v243 offset:2048
	ds_read_b128 v[174:177], v243 offset:3072
	ds_read_b128 v[184:187], v243 offset:4096
	ds_read_b128 v[202:205], v243 offset:5120
	ds_read_b128 v[206:209], v243 offset:6144
	ds_read_b128 v[210:213], v243 offset:7168
	global_load_lds_dwordx4 v[214:215], off
	v_lshl_add_u64 v[214:215], s[28:29], 0, v[200:201]
	s_add_i32 m0, s48, 0xe000
	s_nop 0
	global_load_lds_dwordx4 v[214:215], off
	s_waitcnt vmcnt(8)
	s_waitcnt lgkmcnt(0)
	s_barrier
	s_waitcnt lgkmcnt(0)
	v_mfma_f32_16x16x32_bf16 v[142:145], v[74:77], v[162:165], v[142:145]
	v_mfma_f32_16x16x32_bf16 v[138:141], v[82:85], v[162:165], v[138:141]
	v_mfma_f32_16x16x32_bf16 v[126:129], v[74:77], v[170:173], v[126:129]
	v_mfma_f32_16x16x32_bf16 v[122:125], v[82:85], v[170:173], v[122:125]
	v_mfma_f32_16x16x32_bf16 v[110:113], v[74:77], v[184:187], v[110:113]
	v_mfma_f32_16x16x32_bf16 v[106:109], v[82:85], v[184:187], v[106:109]
	v_mfma_f32_16x16x32_bf16 v[94:97], v[74:77], v[206:209], v[94:97]
	v_mfma_f32_16x16x32_bf16 v[90:93], v[82:85], v[206:209], v[90:93]
	v_mfma_f32_16x16x32_bf16 v[142:145], v[78:81], v[166:169], v[142:145]
	v_mfma_f32_16x16x32_bf16 v[138:141], v[86:89], v[166:169], v[138:141]
	v_mfma_f32_16x16x32_bf16 v[126:129], v[78:81], v[174:177], v[126:129]
	v_mfma_f32_16x16x32_bf16 v[122:125], v[86:89], v[174:177], v[122:125]
	v_mfma_f32_16x16x32_bf16 v[110:113], v[78:81], v[202:205], v[110:113]
	v_mfma_f32_16x16x32_bf16 v[106:109], v[86:89], v[202:205], v[106:109]
	v_mfma_f32_16x16x32_bf16 v[94:97], v[78:81], v[210:213], v[94:97]
	v_mfma_f32_16x16x32_bf16 v[90:93], v[86:89], v[210:213], v[90:93]
	v_mfma_f32_16x16x32_bf16 v[134:137], v[146:149], v[162:165], v[134:137]
	v_mfma_f32_16x16x32_bf16 v[130:133], v[154:157], v[162:165], v[130:133]
	v_mfma_f32_16x16x32_bf16 v[118:121], v[146:149], v[170:173], v[118:121]
	v_mfma_f32_16x16x32_bf16 v[114:117], v[154:157], v[170:173], v[114:117]
	v_mfma_f32_16x16x32_bf16 v[102:105], v[146:149], v[184:187], v[102:105]
	v_mfma_f32_16x16x32_bf16 v[98:101], v[154:157], v[184:187], v[98:101]
	v_mfma_f32_16x16x32_bf16 v[70:73], v[146:149], v[206:209], v[70:73]
	v_mfma_f32_16x16x32_bf16 v[66:69], v[154:157], v[206:209], v[66:69]
	v_mfma_f32_16x16x32_bf16 v[134:137], v[150:153], v[166:169], v[134:137]
	v_mfma_f32_16x16x32_bf16 v[130:133], v[158:161], v[166:169], v[130:133]
	v_mfma_f32_16x16x32_bf16 v[118:121], v[150:153], v[174:177], v[118:121]
	v_mfma_f32_16x16x32_bf16 v[114:117], v[158:161], v[174:177], v[114:117]
	v_mfma_f32_16x16x32_bf16 v[102:105], v[150:153], v[202:205], v[102:105]
	v_mfma_f32_16x16x32_bf16 v[98:101], v[158:161], v[202:205], v[98:101]
	v_mfma_f32_16x16x32_bf16 v[70:73], v[150:153], v[210:213], v[70:73]
	v_mfma_f32_16x16x32_bf16 v[66:69], v[158:161], v[210:213], v[66:69]
	s_barrier
	s_add_i32 s28, s74, s39
	v_lshl_add_u64 v[214:215], s[8:9], 0, v[194:195]
	s_mov_b32 m0, s28
	ds_read_b128 v[162:165], v243 offset:16384
	ds_read_b128 v[166:169], v243 offset:17408
	ds_read_b128 v[170:173], v243 offset:18432
	ds_read_b128 v[174:177], v243 offset:19456
	ds_read_b128 v[184:187], v243 offset:20480
	ds_read_b128 v[202:205], v243 offset:21504
	ds_read_b128 v[206:209], v243 offset:22528
	ds_read_b128 v[210:213], v243 offset:23552
	global_load_lds_dwordx4 v[214:215], off
	s_add_i32 m0, s28, 0x2000
	s_add_u32 s28, s8, 0xb0000
	v_lshl_add_u64 v[216:217], s[8:9], 0, v[190:191]
	s_addc_u32 s29, s9, 0
	s_add_i32 s74, s75, s39
	global_load_lds_dwordx4 v[216:217], off
	v_lshl_add_u64 v[218:219], s[28:29], 0, v[194:195]
	s_mov_b32 m0, s74
	v_lshl_add_u64 v[220:221], s[34:35], 0, v[192:193]
	global_load_lds_dwordx4 v[218:219], off
	v_lshl_add_u64 v[218:219], s[28:29], 0, v[190:191]
	s_add_i32 m0, s74, 0x2000
	s_nop 0
	global_load_lds_dwordx4 v[218:219], off
	v_lshl_add_u64 v[218:219], s[34:35], 0, v[196:197]
	s_mov_b32 m0, s48
	s_nop 0
	global_load_lds_dwordx4 v[218:219], off
	s_mov_b32 m0, s49
	s_nop 0
	global_load_lds_dwordx4 v[220:221], off
	s_waitcnt vmcnt(8)
	s_waitcnt lgkmcnt(0)
	s_barrier
	s_waitcnt lgkmcnt(0)
	v_mfma_f32_16x16x32_bf16 v[62:65], v[74:77], v[162:165], v[62:65]
	v_mfma_f32_16x16x32_bf16 v[58:61], v[82:85], v[162:165], v[58:61]
	v_mfma_f32_16x16x32_bf16 v[46:49], v[74:77], v[170:173], v[46:49]
	v_mfma_f32_16x16x32_bf16 v[42:45], v[82:85], v[170:173], v[42:45]
	v_mfma_f32_16x16x32_bf16 v[30:33], v[74:77], v[184:187], v[30:33]
	v_mfma_f32_16x16x32_bf16 v[26:29], v[82:85], v[184:187], v[26:29]
	v_mfma_f32_16x16x32_bf16 v[18:21], v[74:77], v[206:209], v[18:21]
	v_mfma_f32_16x16x32_bf16 v[10:13], v[82:85], v[206:209], v[10:13]
	v_mfma_f32_16x16x32_bf16 v[62:65], v[78:81], v[166:169], v[62:65]
	v_mfma_f32_16x16x32_bf16 v[58:61], v[86:89], v[166:169], v[58:61]
	v_mfma_f32_16x16x32_bf16 v[46:49], v[78:81], v[174:177], v[46:49]
	v_mfma_f32_16x16x32_bf16 v[42:45], v[86:89], v[174:177], v[42:45]
	v_mfma_f32_16x16x32_bf16 v[30:33], v[78:81], v[202:205], v[30:33]
	v_mfma_f32_16x16x32_bf16 v[26:29], v[86:89], v[202:205], v[26:29]
	v_mfma_f32_16x16x32_bf16 v[18:21], v[78:81], v[210:213], v[18:21]
	v_mfma_f32_16x16x32_bf16 v[10:13], v[86:89], v[210:213], v[10:13]
	v_mfma_f32_16x16x32_bf16 v[54:57], v[146:149], v[162:165], v[54:57]
	v_mfma_f32_16x16x32_bf16 v[50:53], v[154:157], v[162:165], v[50:53]
	v_mfma_f32_16x16x32_bf16 v[38:41], v[146:149], v[170:173], v[38:41]
	v_mfma_f32_16x16x32_bf16 v[34:37], v[154:157], v[170:173], v[34:37]
	v_mfma_f32_16x16x32_bf16 v[22:25], v[146:149], v[184:187], v[22:25]
	v_mfma_f32_16x16x32_bf16 v[14:17], v[154:157], v[184:187], v[14:17]
	v_mfma_f32_16x16x32_bf16 v[6:9], v[146:149], v[206:209], v[6:9]
	v_mfma_f32_16x16x32_bf16 v[2:5], v[154:157], v[206:209], v[2:5]
	v_mfma_f32_16x16x32_bf16 v[54:57], v[150:153], v[166:169], v[54:57]
	v_mfma_f32_16x16x32_bf16 v[50:53], v[158:161], v[166:169], v[50:53]
	v_mfma_f32_16x16x32_bf16 v[38:41], v[150:153], v[174:177], v[38:41]
	v_mfma_f32_16x16x32_bf16 v[34:37], v[158:161], v[174:177], v[34:37]
	v_mfma_f32_16x16x32_bf16 v[22:25], v[150:153], v[202:205], v[22:25]
	v_mfma_f32_16x16x32_bf16 v[14:17], v[158:161], v[202:205], v[14:17]
	v_mfma_f32_16x16x32_bf16 v[6:9], v[150:153], v[210:213], v[6:9]
	v_mfma_f32_16x16x32_bf16 v[2:5], v[158:161], v[210:213], v[2:5]
	s_barrier
	s_add_i32 s74, 0, 0x18000
	s_add_i32 s75, 0, 0x1c000
	v_add_u32_e32 v86, s74, v242
	v_add_u32_e32 v158, s75, v242
	ds_read_b128 v[74:77], v86
	ds_read_b128 v[78:81], v86 offset:1024
	ds_read_b128 v[82:85], v86 offset:2048
	ds_read_b128 v[86:89], v86 offset:3072
	ds_read_b128 v[146:149], v158
	ds_read_b128 v[150:153], v158 offset:1024
	ds_read_b128 v[154:157], v158 offset:2048
	ds_read_b128 v[158:161], v158 offset:3072
	s_add_u32 s28, s34, 0xb0000
	s_addc_u32 s29, s35, 0
	s_mov_b32 m0, s50
	v_lshl_add_u64 v[222:223], s[28:29], 0, v[196:197]
	ds_read_b128 v[162:165], v243 offset:32768
	ds_read_b128 v[166:169], v243 offset:33792
	ds_read_b128 v[170:173], v243 offset:34816
	ds_read_b128 v[174:177], v243 offset:35840
	ds_read_b128 v[184:187], v243 offset:36864
	ds_read_b128 v[202:205], v243 offset:37888
	ds_read_b128 v[206:209], v243 offset:38912
	ds_read_b128 v[210:213], v243 offset:39936
	global_load_lds_dwordx4 v[222:223], off
	v_lshl_add_u64 v[222:223], s[28:29], 0, v[192:193]
	s_mov_b32 m0, s51
	s_nop 0
	global_load_lds_dwordx4 v[222:223], off
	s_waitcnt vmcnt(8)
	s_waitcnt lgkmcnt(0)
	s_barrier
	s_waitcnt lgkmcnt(0)
	v_mfma_f32_16x16x32_bf16 v[142:145], v[74:77], v[162:165], v[142:145]
	v_mfma_f32_16x16x32_bf16 v[138:141], v[82:85], v[162:165], v[138:141]
	v_mfma_f32_16x16x32_bf16 v[126:129], v[74:77], v[170:173], v[126:129]
	v_mfma_f32_16x16x32_bf16 v[122:125], v[82:85], v[170:173], v[122:125]
	v_mfma_f32_16x16x32_bf16 v[110:113], v[74:77], v[184:187], v[110:113]
	v_mfma_f32_16x16x32_bf16 v[106:109], v[82:85], v[184:187], v[106:109]
	v_mfma_f32_16x16x32_bf16 v[94:97], v[74:77], v[206:209], v[94:97]
	v_mfma_f32_16x16x32_bf16 v[90:93], v[82:85], v[206:209], v[90:93]
	v_mfma_f32_16x16x32_bf16 v[142:145], v[78:81], v[166:169], v[142:145]
	v_mfma_f32_16x16x32_bf16 v[138:141], v[86:89], v[166:169], v[138:141]
	v_mfma_f32_16x16x32_bf16 v[126:129], v[78:81], v[174:177], v[126:129]
	v_mfma_f32_16x16x32_bf16 v[122:125], v[86:89], v[174:177], v[122:125]
	v_mfma_f32_16x16x32_bf16 v[110:113], v[78:81], v[202:205], v[110:113]
	v_mfma_f32_16x16x32_bf16 v[106:109], v[86:89], v[202:205], v[106:109]
	v_mfma_f32_16x16x32_bf16 v[94:97], v[78:81], v[210:213], v[94:97]
	v_mfma_f32_16x16x32_bf16 v[90:93], v[86:89], v[210:213], v[90:93]
	v_mfma_f32_16x16x32_bf16 v[134:137], v[146:149], v[162:165], v[134:137]
	v_mfma_f32_16x16x32_bf16 v[130:133], v[154:157], v[162:165], v[130:133]
	v_mfma_f32_16x16x32_bf16 v[118:121], v[146:149], v[170:173], v[118:121]
	v_mfma_f32_16x16x32_bf16 v[114:117], v[154:157], v[170:173], v[114:117]
	v_mfma_f32_16x16x32_bf16 v[102:105], v[146:149], v[184:187], v[102:105]
	v_mfma_f32_16x16x32_bf16 v[98:101], v[154:157], v[184:187], v[98:101]
	v_mfma_f32_16x16x32_bf16 v[70:73], v[146:149], v[206:209], v[70:73]
	v_mfma_f32_16x16x32_bf16 v[66:69], v[154:157], v[206:209], v[66:69]
	v_mfma_f32_16x16x32_bf16 v[134:137], v[150:153], v[166:169], v[134:137]
	v_mfma_f32_16x16x32_bf16 v[130:133], v[158:161], v[166:169], v[130:133]
	v_mfma_f32_16x16x32_bf16 v[118:121], v[150:153], v[174:177], v[118:121]
	v_mfma_f32_16x16x32_bf16 v[114:117], v[158:161], v[174:177], v[114:117]
	v_mfma_f32_16x16x32_bf16 v[102:105], v[150:153], v[202:205], v[102:105]
	v_mfma_f32_16x16x32_bf16 v[98:101], v[158:161], v[202:205], v[98:101]
	v_mfma_f32_16x16x32_bf16 v[70:73], v[150:153], v[210:213], v[70:73]
	v_mfma_f32_16x16x32_bf16 v[66:69], v[158:161], v[210:213], v[66:69]
	s_barrier
	s_add_i32 s28, s74, s39
	v_lshl_add_u64 v[214:215], v[214:215], 0, s[72:73]
	s_mov_b32 m0, s28
	ds_read_b128 v[162:165], v243 offset:49152
	ds_read_b128 v[166:169], v243 offset:50176
	ds_read_b128 v[170:173], v243 offset:51200
	ds_read_b128 v[174:177], v243 offset:52224
	ds_read_b128 v[184:187], v243 offset:53248
	ds_read_b128 v[202:205], v243 offset:54272
	ds_read_b128 v[206:209], v243 offset:55296
	ds_read_b128 v[210:213], v243 offset:56320
	global_load_lds_dwordx4 v[214:215], off
	s_add_i32 m0, s28, 0x2000
	s_add_u32 s8, s8, 0xb0080
	v_lshl_add_u64 v[214:215], v[216:217], 0, s[72:73]
	s_addc_u32 s9, s9, 0
	s_add_i32 s28, s75, s39
	global_load_lds_dwordx4 v[214:215], off
	v_lshl_add_u64 v[214:215], s[8:9], 0, v[194:195]
	s_mov_b32 m0, s28
	s_nop 0
	global_load_lds_dwordx4 v[214:215], off
	v_lshl_add_u64 v[214:215], s[8:9], 0, v[190:191]
	s_add_i32 m0, s28, 0x2000
	s_nop 0
	global_load_lds_dwordx4 v[214:215], off
	v_lshl_add_u64 v[214:215], v[218:219], 0, s[72:73]
	s_mov_b32 m0, s61
	s_nop 0
	global_load_lds_dwordx4 v[214:215], off
	v_lshl_add_u64 v[214:215], v[220:221], 0, s[72:73]
	s_mov_b32 m0, s64
	s_nop 0
	global_load_lds_dwordx4 v[214:215], off
	s_waitcnt vmcnt(8)
	s_waitcnt lgkmcnt(0)
	s_barrier
	s_waitcnt lgkmcnt(0)
	v_mfma_f32_16x16x32_bf16 v[62:65], v[74:77], v[162:165], v[62:65]
	v_mfma_f32_16x16x32_bf16 v[58:61], v[82:85], v[162:165], v[58:61]
	v_mfma_f32_16x16x32_bf16 v[46:49], v[74:77], v[170:173], v[46:49]
	v_mfma_f32_16x16x32_bf16 v[42:45], v[82:85], v[170:173], v[42:45]
	v_mfma_f32_16x16x32_bf16 v[30:33], v[74:77], v[184:187], v[30:33]
	v_mfma_f32_16x16x32_bf16 v[26:29], v[82:85], v[184:187], v[26:29]
	v_mfma_f32_16x16x32_bf16 v[18:21], v[74:77], v[206:209], v[18:21]
	v_mfma_f32_16x16x32_bf16 v[10:13], v[82:85], v[206:209], v[10:13]
	v_mfma_f32_16x16x32_bf16 v[62:65], v[78:81], v[166:169], v[62:65]
	v_mfma_f32_16x16x32_bf16 v[58:61], v[86:89], v[166:169], v[58:61]
	v_mfma_f32_16x16x32_bf16 v[46:49], v[78:81], v[174:177], v[46:49]
	v_mfma_f32_16x16x32_bf16 v[42:45], v[86:89], v[174:177], v[42:45]
	v_mfma_f32_16x16x32_bf16 v[30:33], v[78:81], v[202:205], v[30:33]
	v_mfma_f32_16x16x32_bf16 v[26:29], v[86:89], v[202:205], v[26:29]
	v_mfma_f32_16x16x32_bf16 v[18:21], v[78:81], v[210:213], v[18:21]
	v_mfma_f32_16x16x32_bf16 v[10:13], v[86:89], v[210:213], v[10:13]
	v_mfma_f32_16x16x32_bf16 v[54:57], v[146:149], v[162:165], v[54:57]
	v_mfma_f32_16x16x32_bf16 v[50:53], v[154:157], v[162:165], v[50:53]
	v_mfma_f32_16x16x32_bf16 v[38:41], v[146:149], v[170:173], v[38:41]
	v_mfma_f32_16x16x32_bf16 v[34:37], v[154:157], v[170:173], v[34:37]
	v_mfma_f32_16x16x32_bf16 v[22:25], v[146:149], v[184:187], v[22:25]
	v_mfma_f32_16x16x32_bf16 v[14:17], v[154:157], v[184:187], v[14:17]
	v_mfma_f32_16x16x32_bf16 v[6:9], v[146:149], v[206:209], v[6:9]
	v_mfma_f32_16x16x32_bf16 v[2:5], v[154:157], v[206:209], v[2:5]
	v_mfma_f32_16x16x32_bf16 v[54:57], v[150:153], v[166:169], v[54:57]
	v_mfma_f32_16x16x32_bf16 v[50:53], v[158:161], v[166:169], v[50:53]
	v_mfma_f32_16x16x32_bf16 v[38:41], v[150:153], v[174:177], v[38:41]
	v_mfma_f32_16x16x32_bf16 v[34:37], v[158:161], v[174:177], v[34:37]
	v_mfma_f32_16x16x32_bf16 v[22:25], v[150:153], v[202:205], v[22:25]
	v_mfma_f32_16x16x32_bf16 v[14:17], v[158:161], v[202:205], v[14:17]
	v_mfma_f32_16x16x32_bf16 v[6:9], v[150:153], v[210:213], v[6:9]
	v_mfma_f32_16x16x32_bf16 v[2:5], v[158:161], v[210:213], v[2:5]
	s_barrier
	s_add_i32 s71, s71, 2
	s_add_u32 s69, s69, 0x100
	s_addc_u32 s70, s70, 0
	s_cmp_gt_u32 s71, 41
	s_mov_b64 s[28:29], s[6:7]
	s_cbranch_scc0 .LBB0_1471
	v_mov_b32_e32 v170, v1
	v_mov_b32_e32 v152, v189
	s_cmp_lt_i32 s68, 32
	s_mov_b64 s[6:7], 0
	s_cbranch_scc1 .LBB0_1474
	s_sub_i32 s6, s68, 32
	s_lshr_b32 s6, s6, 2
	s_add_i32 s6, s6, 1
	s_mul_hi_u32 s7, s6, 0x1800
	s_mulk_i32 s6, 0x1800
